# attention: hand-rescheduled subtile bodies (2-deep LDS operand prefetch in QK, V frags fetched before softmax, PV split by key half under exp work), parallel Q staging loads, removed in-loop vmcnt(0)
# speedup vs baseline: 1.0172x; 1.0172x over previous
.LBB0_751:
	v_readfirstlane_b32 s1, v207
	s_lshr_b32 s0, s1, 6
	s_lshl_b32 s37, s36, 8
	s_lshl_b32 s79, s0, 5
	s_add_i32 s37, s79, s37
	v_or_b32_e32 v188, s37, v209
	v_add_u32_e32 v176, s46, v188
	v_lshlrev_b64 v[0:1], 11, v[176:177]
	v_lshl_add_u64 v[4:5], v[182:183], 0, v[0:1]
	global_load_dwordx4 v[144:147], v[4:5], off
	global_load_dwordx4 v[148:151], v[4:5], off offset:32
	global_load_dwordx4 v[152:155], v[4:5], off offset:64
	global_load_dwordx4 v[156:159], v[4:5], off offset:96
	global_load_dwordx4 v[160:163], v[4:5], off offset:128
	global_load_dwordx4 v[164:167], v[4:5], off offset:160
	global_load_dwordx4 v[168:171], v[4:5], off offset:192
	global_load_dwordx4 v[172:175], v[4:5], off offset:224
	s_lshl_b32 s37, s0, 13
	v_add_u32_e32 v189, s37, v211
	s_lshl_b32 s37, s0, 3
	v_or_b32_e32 v16, s37, v212
	v_bitop3_b32 v17, s37, v207, v212 bitop3:0x36
	s_lshr_b32 s1, s1, 5
	v_lshlrev_b32_e32 v16, 11, v16
	v_lshlrev_b32_e32 v17, 4, v17
	s_and_b32 s1, s1, 2
	v_and_or_b32 v176, v17, s70, v16
	v_bitop3_b32 v17, s1, v213, v214 bitop3:0x36
	s_or_b32 s1, s37, 4
	s_lshl_b32 s83, s36, 2
	v_lshl_or_b32 v190, v17, 4, v16
	v_or_b32_e32 v16, s1, v212
	v_bitop3_b32 v17, s1, v207, v212 bitop3:0x36
	s_lshl_b32 s38, s36, 3
	v_lshlrev_b32_e32 v16, 11, v16
	v_lshlrev_b32_e32 v17, 4, v17
	s_bfe_u32 s1, s1, 0x20002
	s_or_b32 s86, s83, 3
	v_and_or_b32 v192, v17, s70, v16
	v_bitop3_b32 v17, s1, v213, v214 bitop3:0x36
	s_add_i32 s84, s0, s38
	s_add_i32 s85, s83, 4
	s_lshl_b32 s1, s86, 17
	s_add_u32 s40, s76, s1
	s_addc_u32 s41, s77, 0
	s_add_u32 s66, s81, s1
	s_addc_u32 s67, s82, 0
	s_lshl_b32 s87, s0, 11
	s_add_i32 s88, s87, 0
	s_lshl_b32 s0, s36, 19
	s_add_i32 s89, s88, 0xc000
	s_or_b32 s90, s87, 0x400
	s_add_i32 s91, s88, 0x400
	s_add_i32 s92, s88, 0xc400
	s_or_b32 s36, s0, 0x40000
	s_mov_b32 m0, s88
	s_add_u32 s0, s76, s36
	s_addc_u32 s1, s77, 0
	s_add_u32 s36, s81, s36
	v_lshl_or_b32 v194, v17, 4, v16
	s_addc_u32 s37, s82, 0
	s_add_i32 s93, s88, 0x4000
	s_add_i32 s94, s71, s87
	s_add_i32 s95, s88, 0x4400
	s_add_i32 s96, s71, s90
	v_mov_b32_e32 v185, v184
	v_mov_b32_e32 v96, v177
	v_mov_b32_e32 v97, v177
	v_mov_b32_e32 v110, v177
	v_mov_b32_e32 v111, v177
	v_mov_b32_e32 v98, v177
	v_mov_b32_e32 v99, v177
	v_mov_b32_e32 v100, v177
	v_mov_b32_e32 v101, v177
	v_mov_b32_e32 v102, v177
	v_mov_b32_e32 v103, v177
	v_mov_b32_e32 v104, v177
	v_mov_b32_e32 v105, v177
	v_mov_b32_e32 v106, v177
	v_mov_b32_e32 v107, v177
	v_mov_b32_e32 v108, v177
	v_mov_b32_e32 v109, v177
	v_mov_b64_e32 v[64:65], v[96:97]
	v_mov_b64_e32 v[80:81], v[96:97]
	v_mov_b64_e32 v[32:33], v[96:97]
	v_mov_b64_e32 v[48:49], v[96:97]
	v_mov_b64_e32 v[126:127], v[110:111]
	v_mov_b32_e32 v191, v177
	v_mov_b32_e32 v193, v177
	v_mov_b32_e32 v195, v177
	s_sub_i32 s97, s79, 64
	s_add_i32 s65, s79, 0xffffffa0
	s_or_b32 s38, s38, 6
	s_add_i32 s39, s79, 0xffffff80
	v_mov_b32_e32 v196, v177
	v_mov_b32_e32 v197, v177
	v_mov_b32_e32 v199, 0xf149f2ca
	v_mov_b32_e32 v201, 0xf149f2ca
	v_mov_b64_e32 v[66:67], v[98:99]
	v_mov_b64_e32 v[68:69], v[100:101]
	v_mov_b64_e32 v[70:71], v[102:103]
	v_mov_b64_e32 v[72:73], v[104:105]
	v_mov_b64_e32 v[74:75], v[106:107]
	v_mov_b64_e32 v[76:77], v[108:109]
	v_mov_b64_e32 v[78:79], v[110:111]
	v_mov_b64_e32 v[82:83], v[98:99]
	v_mov_b64_e32 v[84:85], v[100:101]
	v_mov_b64_e32 v[86:87], v[102:103]
	v_mov_b64_e32 v[88:89], v[104:105]
	v_mov_b64_e32 v[90:91], v[106:107]
	v_mov_b64_e32 v[92:93], v[108:109]
	v_mov_b64_e32 v[94:95], v[110:111]
	v_mov_b64_e32 v[34:35], v[98:99]
	v_mov_b64_e32 v[36:37], v[100:101]
	v_mov_b64_e32 v[38:39], v[102:103]
	v_mov_b64_e32 v[40:41], v[104:105]
	v_mov_b64_e32 v[42:43], v[106:107]
	v_mov_b64_e32 v[44:45], v[108:109]
	v_mov_b64_e32 v[46:47], v[110:111]
	v_mov_b64_e32 v[50:51], v[98:99]
	v_mov_b64_e32 v[52:53], v[100:101]
	v_mov_b64_e32 v[54:55], v[102:103]
	v_mov_b64_e32 v[56:57], v[104:105]
	v_mov_b64_e32 v[58:59], v[106:107]
	v_mov_b64_e32 v[60:61], v[108:109]
	v_mov_b64_e32 v[62:63], v[110:111]
	v_mov_b64_e32 v[124:125], v[108:109]
	v_mov_b64_e32 v[122:123], v[106:107]
	v_mov_b64_e32 v[120:121], v[104:105]
	v_mov_b64_e32 v[118:119], v[102:103]
	v_mov_b64_e32 v[116:117], v[100:101]
	v_mov_b64_e32 v[114:115], v[98:99]
	v_mov_b64_e32 v[112:113], v[96:97]
	v_mov_b32_e32 v0, v210
	global_load_lds_dwordx4 v176, s[40:41]
	s_mov_b32 m0, s89
	v_lshlrev_b32_e32 v0, 3, v0
	global_load_lds_dwordx4 v190, s[66:67]
	s_mov_b32 m0, s91
	v_add_u32_e32 v2, 16, v0
	global_load_lds_dwordx4 v192, s[40:41]
	s_mov_b32 m0, s92
	v_or_b32_e32 v1, 1, v0
	global_load_lds_dwordx4 v194, s[66:67]
	s_mov_b32 m0, s93
	v_or_b32_e32 v4, 3, v0
	global_load_lds_dwordx4 v176, s[0:1]
	s_mov_b32 m0, s94
	v_or_b32_e32 v5, 2, v0
	global_load_lds_dwordx4 v190, s[36:37]
	s_mov_b32 m0, s95
	v_or_b32_e32 v6, 5, v0
	global_load_lds_dwordx4 v192, s[0:1]
	s_mov_b32 m0, s96
	v_or_b32_e32 v7, 4, v0
	global_load_lds_dwordx4 v194, s[36:37]
	s_waitcnt vmcnt(8)
	ds_write_b128 v189, v[144:147]
	ds_write_b128 v189, v[148:151] offset:1024
	ds_write_b128 v189, v[152:155] offset:2048
	ds_write_b128 v189, v[156:159] offset:3072
	ds_write_b128 v189, v[160:163] offset:4096
	ds_write_b128 v189, v[164:167] offset:5120
	ds_write_b128 v189, v[168:171] offset:6144
	ds_write_b128 v189, v[172:175] offset:7168
	v_or_b32_e32 v8, 7, v0
	v_or_b32_e32 v9, 6, v0
	v_add_u32_e32 v3, 17, v0
	v_or_b32_e32 v10, 3, v2
	v_or_b32_e32 v11, 2, v2
	v_or_b32_e32 v12, 5, v2
	v_or_b32_e32 v13, 4, v2
	v_or_b32_e32 v14, 7, v2
	v_or_b32_e32 v15, 6, v2
	v_cvt_f32_i32_e32 v17, v10
	v_cvt_f32_i32_e32 v16, v11
	v_cvt_f32_i32_e32 v11, v12
	v_cvt_f32_i32_e32 v10, v13
	v_cvt_f32_i32_e32 v13, v14
	v_cvt_f32_i32_e32 v12, v15
	v_cvt_f32_i32_e32 v15, v4
	v_cvt_f32_i32_e32 v14, v5
	v_cvt_f32_i32_e32 v5, v6
	v_cvt_f32_i32_e32 v4, v7
	v_cvt_f32_i32_e32 v7, v8
	v_cvt_f32_i32_e32 v6, v9
	v_cvt_f32_i32_e32 v0, v0
	v_cvt_f32_i32_e32 v1, v1
	v_cvt_f32_i32_e32 v3, v3
	v_cvt_f32_i32_e32 v2, v2
	v_pk_mul_f32 v[134:135], v[184:185], v[6:7]
	v_pk_mul_f32 v[132:133], v[184:185], v[4:5]
	v_pk_mul_f32 v[130:131], v[184:185], v[14:15]
	v_pk_mul_f32 v[142:143], v[184:185], v[12:13]
	v_pk_mul_f32 v[140:141], v[184:185], v[10:11]
	v_pk_mul_f32 v[138:139], v[184:185], v[16:17]
	v_pk_mul_f32 v[136:137], v[184:185], v[2:3]
	v_pk_mul_f32 v[128:129], v[186:187], v[0:1]
	v_mov_b64_e32 v[0:1], v[96:97]
	v_mov_b64_e32 v[16:17], v[96:97]
	s_or_b32 s36, s83, 2
	s_or_b32 s37, s83, 1
	v_subrev_u32_e32 v185, s79, v231
	s_add_i32 s66, s79, 0xffffff60
	s_add_i32 s67, s79, 0xffffff40
	s_addk_i32 s79, 0xff20
	s_mov_b32 s40, 0
	s_mov_b32 s41, 0
	v_mov_b64_e32 v[2:3], v[98:99]
	v_mov_b64_e32 v[4:5], v[100:101]
	v_mov_b64_e32 v[6:7], v[102:103]
	v_mov_b64_e32 v[8:9], v[104:105]
	v_mov_b64_e32 v[10:11], v[106:107]
	v_mov_b64_e32 v[12:13], v[108:109]
	v_mov_b64_e32 v[14:15], v[110:111]
	v_mov_b64_e32 v[18:19], v[98:99]
	v_mov_b64_e32 v[20:21], v[100:101]
	v_mov_b64_e32 v[22:23], v[102:103]
	v_mov_b64_e32 v[24:25], v[104:105]
	v_mov_b64_e32 v[26:27], v[106:107]
	v_mov_b64_e32 v[28:29], v[108:109]
	v_mov_b64_e32 v[30:31], v[110:111]
	s_branch .LBB0_754

.LBB0_763:
	ds_read_b128 v[160:163], v237 offset:8192
	ds_read_b128 v[164:167], v189
	ds_read_b128 v[202:205], v235 offset:8192
	ds_read_b128 v[244:247], v189 offset:4096
	ds_read_b128 v[248:251], v236 offset:8192
	ds_read_b128 v[252:255], v189 offset:1024
	s_cmp_lg_u32 s79, s40
	s_waitcnt lgkmcnt(4)
	v_mfma_f32_32x32x16_bf16 v[144:159], v[160:163], v[164:167], v[128:143]
	s_waitcnt lgkmcnt(2)
	v_mfma_f32_32x32x16_bf16 v[160:175], v[202:205], v[244:247], v[128:143]
	ds_read_b128 v[202:205], v234 offset:8192
	ds_read_b128 v[244:247], v189 offset:5120
	s_waitcnt lgkmcnt(2)
	v_mfma_f32_32x32x16_bf16 v[144:159], v[248:251], v[252:255], v[144:159]
	ds_read_b128 v[248:251], v241 offset:8192
	ds_read_b128 v[252:255], v189 offset:2048
	s_waitcnt lgkmcnt(2)
	v_mfma_f32_32x32x16_bf16 v[160:175], v[202:205], v[244:247], v[160:175]
	ds_read_b128 v[202:205], v239 offset:8192
	ds_read_b128 v[244:247], v189 offset:6144
	s_waitcnt lgkmcnt(2)
	v_mfma_f32_32x32x16_bf16 v[144:159], v[248:251], v[252:255], v[144:159]
	ds_read_b128 v[248:251], v240 offset:8192
	ds_read_b128 v[252:255], v189 offset:3072
	s_waitcnt lgkmcnt(2)
	v_mfma_f32_32x32x16_bf16 v[160:175], v[202:205], v[244:247], v[160:175]
	ds_read_b128 v[202:205], v238 offset:8192
	ds_read_b128 v[244:247], v189 offset:7168
	s_waitcnt lgkmcnt(2)
	v_mfma_f32_32x32x16_bf16 v[144:159], v[248:251], v[252:255], v[144:159]
	s_waitcnt lgkmcnt(0)
	v_mfma_f32_32x32x16_bf16 v[160:175], v[202:205], v[244:247], v[160:175]
	ds_read_b64_tr_b16 v[202:203], v216 offset:8192
	ds_read_b64_tr_b16 v[204:205], v218 offset:8192
	ds_read_b64_tr_b16 v[244:245], v220 offset:8192
	ds_read_b64_tr_b16 v[246:247], v222 offset:8192
	ds_read_b64_tr_b16 v[248:249], v224 offset:8192
	ds_read_b64_tr_b16 v[250:251], v226 offset:8192
	ds_read_b64_tr_b16 v[252:253], v228 offset:8192
	ds_read_b64_tr_b16 v[254:255], v230 offset:8192
	s_cbranch_scc1 .Lat1_nomask
	s_nop 2
	v_cndmask_b32_e64 v180, v160, v242, s[2:3]
	v_cndmask_b32_e64 v198, v144, v242, s[2:3]
	v_cndmask_b32_e64 v161, v242, v161, s[4:5]
	v_cndmask_b32_e64 v160, v180, v160, s[4:5]
	v_cndmask_b32_e64 v145, v242, v145, s[4:5]
	v_cndmask_b32_e64 v144, v198, v144, s[4:5]
	v_cndmask_b32_e64 v162, v162, v242, s[6:7]
	v_cndmask_b32_e64 v146, v146, v242, s[6:7]
	v_cndmask_b32_e64 v163, v163, v242, s[8:9]
	v_cndmask_b32_e64 v147, v147, v242, s[8:9]
	v_cndmask_b32_e64 v164, v164, v242, s[10:11]
	v_cndmask_b32_e64 v148, v148, v242, s[10:11]
	v_cndmask_b32_e64 v165, v165, v242, s[12:13]
	v_cndmask_b32_e64 v149, v149, v242, s[12:13]
	v_cndmask_b32_e64 v166, v166, v242, s[14:15]
	v_cndmask_b32_e64 v150, v150, v242, s[14:15]
	v_cndmask_b32_e64 v167, v167, v242, s[16:17]
	v_cndmask_b32_e64 v151, v151, v242, s[16:17]
	v_cndmask_b32_e64 v168, v168, v242, s[18:19]
	v_cndmask_b32_e64 v152, v152, v242, s[18:19]
	v_cndmask_b32_e64 v169, v169, v242, s[20:21]
	v_cndmask_b32_e64 v153, v153, v242, s[20:21]
	v_cndmask_b32_e64 v170, v170, v242, s[22:23]
	v_cndmask_b32_e64 v154, v154, v242, s[22:23]
	v_cndmask_b32_e64 v171, v171, v242, s[24:25]
	v_cndmask_b32_e64 v155, v155, v242, s[24:25]
	v_cndmask_b32_e64 v172, v172, v242, s[26:27]
	v_cndmask_b32_e64 v156, v156, v242, s[26:27]
	v_cndmask_b32_e64 v173, v173, v242, s[28:29]
	v_cndmask_b32_e64 v157, v157, v242, s[28:29]
	v_cndmask_b32_e64 v174, v174, v242, s[30:31]
	v_cndmask_b32_e64 v158, v158, v242, s[30:31]
	v_cndmask_b32_e64 v175, v175, v242, s[34:35]
	v_cndmask_b32_e64 v159, v159, v242, s[34:35]
.Lat1_nomask:
	v_add_u32_e32 v215, s40, v185
	v_add_u32_e32 v215, 0xe0, v215
	v_cvt_f32_i32_e32 v215, v215
	v_mul_f32_e32 v200, v184, v215
	v_max_f32_e32 v217, v144, v145
	v_max_f32_e32 v219, v160, v161
	v_max3_f32 v217, v217, v146, v147
	v_max3_f32 v219, v219, v162, v163
	v_max3_f32 v217, v217, v148, v149
	v_max3_f32 v219, v219, v164, v165
	v_max3_f32 v217, v217, v150, v151
	v_max3_f32 v219, v219, v166, v167
	v_max3_f32 v217, v217, v152, v153
	v_max3_f32 v219, v219, v168, v169
	v_max3_f32 v217, v217, v154, v155
	v_max3_f32 v219, v219, v170, v171
	v_max3_f32 v217, v217, v156, v157
	v_max3_f32 v219, v219, v172, v173
	v_max3_f32 v217, v217, v158, v159
	v_max3_f32 v219, v219, v174, v175
	v_mov_b32_e32 v221, v217
	v_mov_b32_e32 v223, v219
	v_add_f32_e32 v227, 0x41000000, v199
	v_add_f32_e32 v215, 0x41000000, v201
	v_permlane32_swap_b32_e32 v217, v221
	v_permlane32_swap_b32_e32 v219, v223
	v_max_f32_e32 v217, v217, v221
	v_max_f32_e32 v219, v219, v223
	v_add_f32_e32 v225, v200, v217
	v_add_f32_e32 v229, v200, v219
	v_cmp_gt_f32_e32 vcc, v225, v227
	v_cmp_gt_f32_e64 s[0:1], v229, v215
	s_or_b64 vcc, vcc, s[0:1]
	s_cbranch_vccz .Lat1_noresc
	v_max_f32_e32 v217, v199, v225
	v_max_f32_e32 v219, v201, v229
	v_sub_f32_e32 v221, v199, v217
	v_exp_f32_e32 v180, v221
	v_sub_f32_e32 v221, v201, v219
	v_exp_f32_e32 v198, v221
	v_mov_b32_e32 v201, v219
	v_mul_f32_e32 v197, v197, v180
	v_mul_f32_e32 v196, v196, v198
	v_pk_mul_f32 v[112:113], v[112:113], v[180:181] op_sel_hi:[1,0]
	v_pk_mul_f32 v[114:115], v[114:115], v[180:181] op_sel_hi:[1,0]
	v_pk_mul_f32 v[116:117], v[116:117], v[180:181] op_sel_hi:[1,0]
	v_pk_mul_f32 v[118:119], v[118:119], v[180:181] op_sel_hi:[1,0]
	v_pk_mul_f32 v[120:121], v[120:121], v[180:181] op_sel_hi:[1,0]
	v_pk_mul_f32 v[122:123], v[122:123], v[180:181] op_sel_hi:[1,0]
	v_pk_mul_f32 v[124:125], v[124:125], v[180:181] op_sel_hi:[1,0]
	v_pk_mul_f32 v[126:127], v[126:127], v[180:181] op_sel_hi:[1,0]
	v_pk_mul_f32 v[64:65], v[64:65], v[180:181] op_sel_hi:[1,0]
	v_pk_mul_f32 v[66:67], v[66:67], v[180:181] op_sel_hi:[1,0]
	v_pk_mul_f32 v[68:69], v[68:69], v[180:181] op_sel_hi:[1,0]
	v_pk_mul_f32 v[70:71], v[70:71], v[180:181] op_sel_hi:[1,0]
	v_pk_mul_f32 v[72:73], v[72:73], v[180:181] op_sel_hi:[1,0]
	v_pk_mul_f32 v[74:75], v[74:75], v[180:181] op_sel_hi:[1,0]
	v_pk_mul_f32 v[76:77], v[76:77], v[180:181] op_sel_hi:[1,0]
	v_pk_mul_f32 v[78:79], v[78:79], v[180:181] op_sel_hi:[1,0]
	v_pk_mul_f32 v[32:33], v[32:33], v[180:181] op_sel_hi:[1,0]
	v_pk_mul_f32 v[34:35], v[34:35], v[180:181] op_sel_hi:[1,0]
	v_pk_mul_f32 v[36:37], v[36:37], v[180:181] op_sel_hi:[1,0]
	v_pk_mul_f32 v[38:39], v[38:39], v[180:181] op_sel_hi:[1,0]
	v_pk_mul_f32 v[40:41], v[40:41], v[180:181] op_sel_hi:[1,0]
	v_pk_mul_f32 v[42:43], v[42:43], v[180:181] op_sel_hi:[1,0]
	v_pk_mul_f32 v[44:45], v[44:45], v[180:181] op_sel_hi:[1,0]
	v_pk_mul_f32 v[46:47], v[46:47], v[180:181] op_sel_hi:[1,0]
	v_pk_mul_f32 v[0:1], v[0:1], v[180:181] op_sel_hi:[1,0]
	v_pk_mul_f32 v[2:3], v[2:3], v[180:181] op_sel_hi:[1,0]
	v_pk_mul_f32 v[4:5], v[4:5], v[180:181] op_sel_hi:[1,0]
	v_pk_mul_f32 v[6:7], v[6:7], v[180:181] op_sel_hi:[1,0]
	v_pk_mul_f32 v[8:9], v[8:9], v[180:181] op_sel_hi:[1,0]
	v_pk_mul_f32 v[10:11], v[10:11], v[180:181] op_sel_hi:[1,0]
	v_pk_mul_f32 v[12:13], v[12:13], v[180:181] op_sel_hi:[1,0]
	v_pk_mul_f32 v[14:15], v[14:15], v[180:181] op_sel_hi:[1,0]
	v_pk_mul_f32 v[96:97], v[96:97], v[198:199] op_sel_hi:[1,0]
	v_pk_mul_f32 v[98:99], v[98:99], v[198:199] op_sel_hi:[1,0]
	v_pk_mul_f32 v[100:101], v[100:101], v[198:199] op_sel_hi:[1,0]
	v_pk_mul_f32 v[102:103], v[102:103], v[198:199] op_sel_hi:[1,0]
	v_pk_mul_f32 v[104:105], v[104:105], v[198:199] op_sel_hi:[1,0]
	v_pk_mul_f32 v[106:107], v[106:107], v[198:199] op_sel_hi:[1,0]
	v_pk_mul_f32 v[108:109], v[108:109], v[198:199] op_sel_hi:[1,0]
	v_pk_mul_f32 v[110:111], v[110:111], v[198:199] op_sel_hi:[1,0]
	v_pk_mul_f32 v[80:81], v[80:81], v[198:199] op_sel_hi:[1,0]
	v_pk_mul_f32 v[82:83], v[82:83], v[198:199] op_sel_hi:[1,0]
	v_pk_mul_f32 v[84:85], v[84:85], v[198:199] op_sel_hi:[1,0]
	v_pk_mul_f32 v[86:87], v[86:87], v[198:199] op_sel_hi:[1,0]
	v_pk_mul_f32 v[88:89], v[88:89], v[198:199] op_sel_hi:[1,0]
	v_pk_mul_f32 v[90:91], v[90:91], v[198:199] op_sel_hi:[1,0]
	v_pk_mul_f32 v[92:93], v[92:93], v[198:199] op_sel_hi:[1,0]
	v_pk_mul_f32 v[94:95], v[94:95], v[198:199] op_sel_hi:[1,0]
	v_pk_mul_f32 v[48:49], v[48:49], v[198:199] op_sel_hi:[1,0]
	v_pk_mul_f32 v[50:51], v[50:51], v[198:199] op_sel_hi:[1,0]
	v_pk_mul_f32 v[52:53], v[52:53], v[198:199] op_sel_hi:[1,0]
	v_pk_mul_f32 v[54:55], v[54:55], v[198:199] op_sel_hi:[1,0]
	v_pk_mul_f32 v[56:57], v[56:57], v[198:199] op_sel_hi:[1,0]
	v_pk_mul_f32 v[58:59], v[58:59], v[198:199] op_sel_hi:[1,0]
	v_pk_mul_f32 v[60:61], v[60:61], v[198:199] op_sel_hi:[1,0]
	v_pk_mul_f32 v[62:63], v[62:63], v[198:199] op_sel_hi:[1,0]
	v_pk_mul_f32 v[16:17], v[16:17], v[198:199] op_sel_hi:[1,0]
	v_pk_mul_f32 v[18:19], v[18:19], v[198:199] op_sel_hi:[1,0]
	v_pk_mul_f32 v[20:21], v[20:21], v[198:199] op_sel_hi:[1,0]
	v_pk_mul_f32 v[22:23], v[22:23], v[198:199] op_sel_hi:[1,0]
	v_pk_mul_f32 v[24:25], v[24:25], v[198:199] op_sel_hi:[1,0]
	v_pk_mul_f32 v[26:27], v[26:27], v[198:199] op_sel_hi:[1,0]
	v_pk_mul_f32 v[28:29], v[28:29], v[198:199] op_sel_hi:[1,0]
	v_pk_mul_f32 v[30:31], v[30:31], v[198:199] op_sel_hi:[1,0]
	v_mov_b32_e32 v199, v217
.Lat1_noresc:
	v_sub_f32_e32 v180, v200, v199
	v_sub_f32_e32 v198, v200, v201
	v_add_f32_e32 v144, v144, v180
	v_add_f32_e32 v160, v160, v198
	v_exp_f32_e32 v144, v144
	v_exp_f32_e32 v160, v160
	v_add_f32_e32 v145, v145, v180
	v_add_f32_e32 v161, v161, v198
	v_exp_f32_e32 v145, v145
	v_exp_f32_e32 v161, v161
	v_add_f32_e32 v146, v146, v180
	v_add_f32_e32 v162, v162, v198
	v_exp_f32_e32 v146, v146
	v_exp_f32_e32 v162, v162
	v_add_f32_e32 v147, v147, v180
	v_add_f32_e32 v163, v163, v198
	v_exp_f32_e32 v147, v147
	v_exp_f32_e32 v163, v163
	v_add_f32_e32 v148, v148, v180
	v_add_f32_e32 v164, v164, v198
	v_exp_f32_e32 v148, v148
	v_exp_f32_e32 v164, v164
	v_add_f32_e32 v149, v149, v180
	v_add_f32_e32 v165, v165, v198
	v_exp_f32_e32 v149, v149
	v_exp_f32_e32 v165, v165
	v_add_f32_e32 v150, v150, v180
	v_add_f32_e32 v166, v166, v198
	v_exp_f32_e32 v150, v150
	v_exp_f32_e32 v166, v166
	v_add_f32_e32 v151, v151, v180
	v_add_f32_e32 v167, v167, v198
	v_exp_f32_e32 v151, v151
	v_exp_f32_e32 v167, v167
	v_add_f32_e32 v215, v144, v145
	v_add_f32_e32 v217, v160, v161
	v_add_f32_e32 v215, v215, v146
	v_add_f32_e32 v217, v217, v162
	v_add_f32_e32 v215, v215, v147
	v_add_f32_e32 v217, v217, v163
	v_add_f32_e32 v215, v215, v148
	v_add_f32_e32 v217, v217, v164
	v_add_f32_e32 v215, v215, v149
	v_add_f32_e32 v217, v217, v165
	v_add_f32_e32 v215, v215, v150
	v_add_f32_e32 v217, v217, v166
	v_add_f32_e32 v215, v215, v151
	v_add_f32_e32 v217, v217, v167
	v_cvt_pk_bf16_f32 v144, v144, v145
	v_cvt_pk_bf16_f32 v160, v160, v161
	v_cvt_pk_bf16_f32 v145, v146, v147
	v_cvt_pk_bf16_f32 v161, v162, v163
	v_cvt_pk_bf16_f32 v146, v148, v149
	v_cvt_pk_bf16_f32 v162, v164, v165
	v_cvt_pk_bf16_f32 v147, v150, v151
	v_cvt_pk_bf16_f32 v163, v166, v167
	ds_read_b64_tr_b16 v[148:149], v216 offset:12288
	ds_read_b64_tr_b16 v[150:151], v218 offset:12288
	ds_read_b64_tr_b16 v[164:165], v220 offset:12288
	ds_read_b64_tr_b16 v[166:167], v222 offset:12288
	s_waitcnt lgkmcnt(4)
	v_mfma_f32_32x32x16_bf16 v[112:127], v[202:205], v[144:147], v[112:127]
	v_add_f32_e32 v152, v152, v180
	v_add_f32_e32 v168, v168, v198
	v_exp_f32_e32 v152, v152
	v_exp_f32_e32 v168, v168
	v_add_f32_e32 v153, v153, v180
	v_add_f32_e32 v169, v169, v198
	v_exp_f32_e32 v153, v153
	v_mfma_f32_32x32x16_bf16 v[96:111], v[202:205], v[160:163], v[96:111]
	v_exp_f32_e32 v169, v169
	v_add_f32_e32 v154, v154, v180
	v_add_f32_e32 v170, v170, v198
	v_exp_f32_e32 v154, v154
	v_exp_f32_e32 v170, v170
	v_add_f32_e32 v155, v155, v180
	v_add_f32_e32 v171, v171, v198
	ds_read_b64_tr_b16 v[202:203], v224 offset:12288
	ds_read_b64_tr_b16 v[204:205], v226 offset:12288
	v_mfma_f32_32x32x16_bf16 v[64:79], v[244:247], v[144:147], v[64:79]
	v_exp_f32_e32 v155, v155
	v_exp_f32_e32 v171, v171
	v_add_f32_e32 v156, v156, v180
	v_add_f32_e32 v172, v172, v198
	v_exp_f32_e32 v156, v156
	v_exp_f32_e32 v172, v172
	v_add_f32_e32 v157, v157, v180
	v_mfma_f32_32x32x16_bf16 v[80:95], v[244:247], v[160:163], v[80:95]
	v_add_f32_e32 v173, v173, v198
	v_exp_f32_e32 v157, v157
	v_exp_f32_e32 v173, v173
	v_add_f32_e32 v158, v158, v180
	v_add_f32_e32 v174, v174, v198
	v_exp_f32_e32 v158, v158
	v_exp_f32_e32 v174, v174
	ds_read_b64_tr_b16 v[244:245], v228 offset:12288
	ds_read_b64_tr_b16 v[246:247], v230 offset:12288
	v_mfma_f32_32x32x16_bf16 v[32:47], v[248:251], v[144:147], v[32:47]
	v_add_f32_e32 v159, v159, v180
	v_add_f32_e32 v175, v175, v198
	v_exp_f32_e32 v159, v159
	v_exp_f32_e32 v175, v175
	v_add_f32_e32 v215, v215, v152
	v_add_f32_e32 v217, v217, v168
	v_add_f32_e32 v215, v215, v153
	v_mfma_f32_32x32x16_bf16 v[48:63], v[248:251], v[160:163], v[48:63]
	v_add_f32_e32 v217, v217, v169
	v_add_f32_e32 v215, v215, v154
	v_add_f32_e32 v217, v217, v170
	v_add_f32_e32 v215, v215, v155
	v_add_f32_e32 v217, v217, v171
	v_add_f32_e32 v215, v215, v156
	v_add_f32_e32 v217, v217, v172
	v_mfma_f32_32x32x16_bf16 v[0:15], v[252:255], v[144:147], v[0:15]
	v_add_f32_e32 v215, v215, v157
	v_add_f32_e32 v217, v217, v173
	v_add_f32_e32 v215, v215, v158
	v_add_f32_e32 v217, v217, v174
	v_add_f32_e32 v215, v215, v159
	v_add_f32_e32 v217, v217, v175
	v_cvt_pk_bf16_f32 v152, v152, v153
	v_mfma_f32_32x32x16_bf16 v[16:31], v[252:255], v[160:163], v[16:31]
	v_cvt_pk_bf16_f32 v168, v168, v169
	v_cvt_pk_bf16_f32 v153, v154, v155
	v_cvt_pk_bf16_f32 v169, v170, v171
	v_cvt_pk_bf16_f32 v154, v156, v157
	v_cvt_pk_bf16_f32 v170, v172, v173
	v_cvt_pk_bf16_f32 v155, v158, v159
	v_cvt_pk_bf16_f32 v171, v174, v175
	v_add_f32_e32 v197, v197, v215
	v_add_f32_e32 v196, v196, v217
	s_waitcnt lgkmcnt(6)
	v_mfma_f32_32x32x16_bf16 v[112:127], v[148:151], v[152:155], v[112:127]
	v_mfma_f32_32x32x16_bf16 v[96:111], v[148:151], v[168:171], v[96:111]
	s_waitcnt lgkmcnt(4)
	v_mfma_f32_32x32x16_bf16 v[64:79], v[164:167], v[152:155], v[64:79]
	v_mfma_f32_32x32x16_bf16 v[80:95], v[164:167], v[168:171], v[80:95]
	s_waitcnt lgkmcnt(2)
	v_mfma_f32_32x32x16_bf16 v[32:47], v[202:205], v[152:155], v[32:47]
	v_mfma_f32_32x32x16_bf16 v[48:63], v[202:205], v[168:171], v[48:63]
	s_waitcnt lgkmcnt(0)
	v_mfma_f32_32x32x16_bf16 v[0:15], v[244:247], v[152:155], v[0:15]
	v_mfma_f32_32x32x16_bf16 v[16:31], v[244:247], v[168:171], v[16:31]
	s_cmp_gt_i32 s38, s84
	s_cbranch_scc1 .LBB0_759
.LBB0_768:
	ds_read_b128 v[160:163], v237
	ds_read_b128 v[164:167], v189
	ds_read_b128 v[202:205], v235
	ds_read_b128 v[244:247], v189 offset:4096
	ds_read_b128 v[248:251], v236
	ds_read_b128 v[252:255], v189 offset:1024
	s_cmp_lg_u32 s67, s40
	s_waitcnt lgkmcnt(4)
	v_mfma_f32_32x32x16_bf16 v[144:159], v[160:163], v[164:167], v[128:143]
	s_waitcnt lgkmcnt(2)
	v_mfma_f32_32x32x16_bf16 v[160:175], v[202:205], v[244:247], v[128:143]
	ds_read_b128 v[202:205], v234
	ds_read_b128 v[244:247], v189 offset:5120
	s_waitcnt lgkmcnt(2)
	v_mfma_f32_32x32x16_bf16 v[144:159], v[248:251], v[252:255], v[144:159]
	ds_read_b128 v[248:251], v241
	ds_read_b128 v[252:255], v189 offset:2048
	s_waitcnt lgkmcnt(2)
	v_mfma_f32_32x32x16_bf16 v[160:175], v[202:205], v[244:247], v[160:175]
	ds_read_b128 v[202:205], v239
	ds_read_b128 v[244:247], v189 offset:6144
	s_waitcnt lgkmcnt(2)
	v_mfma_f32_32x32x16_bf16 v[144:159], v[248:251], v[252:255], v[144:159]
	ds_read_b128 v[248:251], v240
	ds_read_b128 v[252:255], v189 offset:3072
	s_waitcnt lgkmcnt(2)
	v_mfma_f32_32x32x16_bf16 v[160:175], v[202:205], v[244:247], v[160:175]
	ds_read_b128 v[202:205], v238
	ds_read_b128 v[244:247], v189 offset:7168
	s_waitcnt lgkmcnt(2)
	v_mfma_f32_32x32x16_bf16 v[144:159], v[248:251], v[252:255], v[144:159]
	s_waitcnt lgkmcnt(0)
	v_mfma_f32_32x32x16_bf16 v[160:175], v[202:205], v[244:247], v[160:175]
	ds_read_b64_tr_b16 v[202:203], v216
	ds_read_b64_tr_b16 v[204:205], v218
	ds_read_b64_tr_b16 v[244:245], v220
	ds_read_b64_tr_b16 v[246:247], v222
	ds_read_b64_tr_b16 v[248:249], v224
	ds_read_b64_tr_b16 v[250:251], v226
	ds_read_b64_tr_b16 v[252:253], v228
	ds_read_b64_tr_b16 v[254:255], v230
	s_cbranch_scc1 .Lat2_nomask
	s_nop 2
	v_cndmask_b32_e64 v180, v160, v242, s[2:3]
	v_cndmask_b32_e64 v198, v144, v242, s[2:3]
	v_cndmask_b32_e64 v161, v242, v161, s[4:5]
	v_cndmask_b32_e64 v160, v180, v160, s[4:5]
	v_cndmask_b32_e64 v145, v242, v145, s[4:5]
	v_cndmask_b32_e64 v144, v198, v144, s[4:5]
	v_cndmask_b32_e64 v162, v162, v242, s[6:7]
	v_cndmask_b32_e64 v146, v146, v242, s[6:7]
	v_cndmask_b32_e64 v163, v163, v242, s[8:9]
	v_cndmask_b32_e64 v147, v147, v242, s[8:9]
	v_cndmask_b32_e64 v164, v164, v242, s[10:11]
	v_cndmask_b32_e64 v148, v148, v242, s[10:11]
	v_cndmask_b32_e64 v165, v165, v242, s[12:13]
	v_cndmask_b32_e64 v149, v149, v242, s[12:13]
	v_cndmask_b32_e64 v166, v166, v242, s[14:15]
	v_cndmask_b32_e64 v150, v150, v242, s[14:15]
	v_cndmask_b32_e64 v167, v167, v242, s[16:17]
	v_cndmask_b32_e64 v151, v151, v242, s[16:17]
	v_cndmask_b32_e64 v168, v168, v242, s[18:19]
	v_cndmask_b32_e64 v152, v152, v242, s[18:19]
	v_cndmask_b32_e64 v169, v169, v242, s[20:21]
	v_cndmask_b32_e64 v153, v153, v242, s[20:21]
	v_cndmask_b32_e64 v170, v170, v242, s[22:23]
	v_cndmask_b32_e64 v154, v154, v242, s[22:23]
	v_cndmask_b32_e64 v171, v171, v242, s[24:25]
	v_cndmask_b32_e64 v155, v155, v242, s[24:25]
	v_cndmask_b32_e64 v172, v172, v242, s[26:27]
	v_cndmask_b32_e64 v156, v156, v242, s[26:27]
	v_cndmask_b32_e64 v173, v173, v242, s[28:29]
	v_cndmask_b32_e64 v157, v157, v242, s[28:29]
	v_cndmask_b32_e64 v174, v174, v242, s[30:31]
	v_cndmask_b32_e64 v158, v158, v242, s[30:31]
	v_cndmask_b32_e64 v175, v175, v242, s[34:35]
	v_cndmask_b32_e64 v159, v159, v242, s[34:35]
.Lat2_nomask:
	v_add_u32_e32 v215, s40, v185
	v_add_u32_e32 v215, 0xc0, v215
	v_cvt_f32_i32_e32 v215, v215
	v_mul_f32_e32 v200, v184, v215
	v_max_f32_e32 v217, v144, v145
	v_max_f32_e32 v219, v160, v161
	v_max3_f32 v217, v217, v146, v147
	v_max3_f32 v219, v219, v162, v163
	v_max3_f32 v217, v217, v148, v149
	v_max3_f32 v219, v219, v164, v165
	v_max3_f32 v217, v217, v150, v151
	v_max3_f32 v219, v219, v166, v167
	v_max3_f32 v217, v217, v152, v153
	v_max3_f32 v219, v219, v168, v169
	v_max3_f32 v217, v217, v154, v155
	v_max3_f32 v219, v219, v170, v171
	v_max3_f32 v217, v217, v156, v157
	v_max3_f32 v219, v219, v172, v173
	v_max3_f32 v217, v217, v158, v159
	v_max3_f32 v219, v219, v174, v175
	v_mov_b32_e32 v221, v217
	v_mov_b32_e32 v223, v219
	v_add_f32_e32 v227, 0x41000000, v199
	v_add_f32_e32 v215, 0x41000000, v201
	v_permlane32_swap_b32_e32 v217, v221
	v_permlane32_swap_b32_e32 v219, v223
	v_max_f32_e32 v217, v217, v221
	v_max_f32_e32 v219, v219, v223
	v_add_f32_e32 v225, v200, v217
	v_add_f32_e32 v229, v200, v219
	v_cmp_gt_f32_e32 vcc, v225, v227
	v_cmp_gt_f32_e64 s[0:1], v229, v215
	s_or_b64 vcc, vcc, s[0:1]
	s_cbranch_vccz .Lat2_noresc
	v_max_f32_e32 v217, v199, v225
	v_max_f32_e32 v219, v201, v229
	v_sub_f32_e32 v221, v199, v217
	v_exp_f32_e32 v180, v221
	v_sub_f32_e32 v221, v201, v219
	v_exp_f32_e32 v198, v221
	v_mov_b32_e32 v201, v219
	v_mul_f32_e32 v197, v197, v180
	v_mul_f32_e32 v196, v196, v198
	v_pk_mul_f32 v[112:113], v[112:113], v[180:181] op_sel_hi:[1,0]
	v_pk_mul_f32 v[114:115], v[114:115], v[180:181] op_sel_hi:[1,0]
	v_pk_mul_f32 v[116:117], v[116:117], v[180:181] op_sel_hi:[1,0]
	v_pk_mul_f32 v[118:119], v[118:119], v[180:181] op_sel_hi:[1,0]
	v_pk_mul_f32 v[120:121], v[120:121], v[180:181] op_sel_hi:[1,0]
	v_pk_mul_f32 v[122:123], v[122:123], v[180:181] op_sel_hi:[1,0]
	v_pk_mul_f32 v[124:125], v[124:125], v[180:181] op_sel_hi:[1,0]
	v_pk_mul_f32 v[126:127], v[126:127], v[180:181] op_sel_hi:[1,0]
	v_pk_mul_f32 v[64:65], v[64:65], v[180:181] op_sel_hi:[1,0]
	v_pk_mul_f32 v[66:67], v[66:67], v[180:181] op_sel_hi:[1,0]
	v_pk_mul_f32 v[68:69], v[68:69], v[180:181] op_sel_hi:[1,0]
	v_pk_mul_f32 v[70:71], v[70:71], v[180:181] op_sel_hi:[1,0]
	v_pk_mul_f32 v[72:73], v[72:73], v[180:181] op_sel_hi:[1,0]
	v_pk_mul_f32 v[74:75], v[74:75], v[180:181] op_sel_hi:[1,0]
	v_pk_mul_f32 v[76:77], v[76:77], v[180:181] op_sel_hi:[1,0]
	v_pk_mul_f32 v[78:79], v[78:79], v[180:181] op_sel_hi:[1,0]
	v_pk_mul_f32 v[32:33], v[32:33], v[180:181] op_sel_hi:[1,0]
	v_pk_mul_f32 v[34:35], v[34:35], v[180:181] op_sel_hi:[1,0]
	v_pk_mul_f32 v[36:37], v[36:37], v[180:181] op_sel_hi:[1,0]
	v_pk_mul_f32 v[38:39], v[38:39], v[180:181] op_sel_hi:[1,0]
	v_pk_mul_f32 v[40:41], v[40:41], v[180:181] op_sel_hi:[1,0]
	v_pk_mul_f32 v[42:43], v[42:43], v[180:181] op_sel_hi:[1,0]
	v_pk_mul_f32 v[44:45], v[44:45], v[180:181] op_sel_hi:[1,0]
	v_pk_mul_f32 v[46:47], v[46:47], v[180:181] op_sel_hi:[1,0]
	v_pk_mul_f32 v[0:1], v[0:1], v[180:181] op_sel_hi:[1,0]
	v_pk_mul_f32 v[2:3], v[2:3], v[180:181] op_sel_hi:[1,0]
	v_pk_mul_f32 v[4:5], v[4:5], v[180:181] op_sel_hi:[1,0]
	v_pk_mul_f32 v[6:7], v[6:7], v[180:181] op_sel_hi:[1,0]
	v_pk_mul_f32 v[8:9], v[8:9], v[180:181] op_sel_hi:[1,0]
	v_pk_mul_f32 v[10:11], v[10:11], v[180:181] op_sel_hi:[1,0]
	v_pk_mul_f32 v[12:13], v[12:13], v[180:181] op_sel_hi:[1,0]
	v_pk_mul_f32 v[14:15], v[14:15], v[180:181] op_sel_hi:[1,0]
	v_pk_mul_f32 v[96:97], v[96:97], v[198:199] op_sel_hi:[1,0]
	v_pk_mul_f32 v[98:99], v[98:99], v[198:199] op_sel_hi:[1,0]
	v_pk_mul_f32 v[100:101], v[100:101], v[198:199] op_sel_hi:[1,0]
	v_pk_mul_f32 v[102:103], v[102:103], v[198:199] op_sel_hi:[1,0]
	v_pk_mul_f32 v[104:105], v[104:105], v[198:199] op_sel_hi:[1,0]
	v_pk_mul_f32 v[106:107], v[106:107], v[198:199] op_sel_hi:[1,0]
	v_pk_mul_f32 v[108:109], v[108:109], v[198:199] op_sel_hi:[1,0]
	v_pk_mul_f32 v[110:111], v[110:111], v[198:199] op_sel_hi:[1,0]
	v_pk_mul_f32 v[80:81], v[80:81], v[198:199] op_sel_hi:[1,0]
	v_pk_mul_f32 v[82:83], v[82:83], v[198:199] op_sel_hi:[1,0]
	v_pk_mul_f32 v[84:85], v[84:85], v[198:199] op_sel_hi:[1,0]
	v_pk_mul_f32 v[86:87], v[86:87], v[198:199] op_sel_hi:[1,0]
	v_pk_mul_f32 v[88:89], v[88:89], v[198:199] op_sel_hi:[1,0]
	v_pk_mul_f32 v[90:91], v[90:91], v[198:199] op_sel_hi:[1,0]
	v_pk_mul_f32 v[92:93], v[92:93], v[198:199] op_sel_hi:[1,0]
	v_pk_mul_f32 v[94:95], v[94:95], v[198:199] op_sel_hi:[1,0]
	v_pk_mul_f32 v[48:49], v[48:49], v[198:199] op_sel_hi:[1,0]
	v_pk_mul_f32 v[50:51], v[50:51], v[198:199] op_sel_hi:[1,0]
	v_pk_mul_f32 v[52:53], v[52:53], v[198:199] op_sel_hi:[1,0]
	v_pk_mul_f32 v[54:55], v[54:55], v[198:199] op_sel_hi:[1,0]
	v_pk_mul_f32 v[56:57], v[56:57], v[198:199] op_sel_hi:[1,0]
	v_pk_mul_f32 v[58:59], v[58:59], v[198:199] op_sel_hi:[1,0]
	v_pk_mul_f32 v[60:61], v[60:61], v[198:199] op_sel_hi:[1,0]
	v_pk_mul_f32 v[62:63], v[62:63], v[198:199] op_sel_hi:[1,0]
	v_pk_mul_f32 v[16:17], v[16:17], v[198:199] op_sel_hi:[1,0]
	v_pk_mul_f32 v[18:19], v[18:19], v[198:199] op_sel_hi:[1,0]
	v_pk_mul_f32 v[20:21], v[20:21], v[198:199] op_sel_hi:[1,0]
	v_pk_mul_f32 v[22:23], v[22:23], v[198:199] op_sel_hi:[1,0]
	v_pk_mul_f32 v[24:25], v[24:25], v[198:199] op_sel_hi:[1,0]
	v_pk_mul_f32 v[26:27], v[26:27], v[198:199] op_sel_hi:[1,0]
	v_pk_mul_f32 v[28:29], v[28:29], v[198:199] op_sel_hi:[1,0]
	v_pk_mul_f32 v[30:31], v[30:31], v[198:199] op_sel_hi:[1,0]
	v_mov_b32_e32 v199, v217
.Lat2_noresc:
	v_sub_f32_e32 v180, v200, v199
	v_sub_f32_e32 v198, v200, v201
	v_add_f32_e32 v144, v144, v180
	v_add_f32_e32 v160, v160, v198
	v_exp_f32_e32 v144, v144
	v_exp_f32_e32 v160, v160
	v_add_f32_e32 v145, v145, v180
	v_add_f32_e32 v161, v161, v198
	v_exp_f32_e32 v145, v145
	v_exp_f32_e32 v161, v161
	v_add_f32_e32 v146, v146, v180
	v_add_f32_e32 v162, v162, v198
	v_exp_f32_e32 v146, v146
	v_exp_f32_e32 v162, v162
	v_add_f32_e32 v147, v147, v180
	v_add_f32_e32 v163, v163, v198
	v_exp_f32_e32 v147, v147
	v_exp_f32_e32 v163, v163
	v_add_f32_e32 v148, v148, v180
	v_add_f32_e32 v164, v164, v198
	v_exp_f32_e32 v148, v148
	v_exp_f32_e32 v164, v164
	v_add_f32_e32 v149, v149, v180
	v_add_f32_e32 v165, v165, v198
	v_exp_f32_e32 v149, v149
	v_exp_f32_e32 v165, v165
	v_add_f32_e32 v150, v150, v180
	v_add_f32_e32 v166, v166, v198
	v_exp_f32_e32 v150, v150
	v_exp_f32_e32 v166, v166
	v_add_f32_e32 v151, v151, v180
	v_add_f32_e32 v167, v167, v198
	v_exp_f32_e32 v151, v151
	v_exp_f32_e32 v167, v167
	v_add_f32_e32 v215, v144, v145
	v_add_f32_e32 v217, v160, v161
	v_add_f32_e32 v215, v215, v146
	v_add_f32_e32 v217, v217, v162
	v_add_f32_e32 v215, v215, v147
	v_add_f32_e32 v217, v217, v163
	v_add_f32_e32 v215, v215, v148
	v_add_f32_e32 v217, v217, v164
	v_add_f32_e32 v215, v215, v149
	v_add_f32_e32 v217, v217, v165
	v_add_f32_e32 v215, v215, v150
	v_add_f32_e32 v217, v217, v166
	v_add_f32_e32 v215, v215, v151
	v_add_f32_e32 v217, v217, v167
	v_cvt_pk_bf16_f32 v144, v144, v145
	v_cvt_pk_bf16_f32 v160, v160, v161
	v_cvt_pk_bf16_f32 v145, v146, v147
	v_cvt_pk_bf16_f32 v161, v162, v163
	v_cvt_pk_bf16_f32 v146, v148, v149
	v_cvt_pk_bf16_f32 v162, v164, v165
	v_cvt_pk_bf16_f32 v147, v150, v151
	v_cvt_pk_bf16_f32 v163, v166, v167
	ds_read_b64_tr_b16 v[148:149], v216 offset:4096
	ds_read_b64_tr_b16 v[150:151], v218 offset:4096
	ds_read_b64_tr_b16 v[164:165], v220 offset:4096
	ds_read_b64_tr_b16 v[166:167], v222 offset:4096
	s_waitcnt lgkmcnt(4)
	v_mfma_f32_32x32x16_bf16 v[112:127], v[202:205], v[144:147], v[112:127]
	v_add_f32_e32 v152, v152, v180
	v_add_f32_e32 v168, v168, v198
	v_exp_f32_e32 v152, v152
	v_exp_f32_e32 v168, v168
	v_add_f32_e32 v153, v153, v180
	v_add_f32_e32 v169, v169, v198
	v_exp_f32_e32 v153, v153
	v_mfma_f32_32x32x16_bf16 v[96:111], v[202:205], v[160:163], v[96:111]
	v_exp_f32_e32 v169, v169
	v_add_f32_e32 v154, v154, v180
	v_add_f32_e32 v170, v170, v198
	v_exp_f32_e32 v154, v154
	v_exp_f32_e32 v170, v170
	v_add_f32_e32 v155, v155, v180
	v_add_f32_e32 v171, v171, v198
	ds_read_b64_tr_b16 v[202:203], v224 offset:4096
	ds_read_b64_tr_b16 v[204:205], v226 offset:4096
	v_mfma_f32_32x32x16_bf16 v[64:79], v[244:247], v[144:147], v[64:79]
	v_exp_f32_e32 v155, v155
	v_exp_f32_e32 v171, v171
	v_add_f32_e32 v156, v156, v180
	v_add_f32_e32 v172, v172, v198
	v_exp_f32_e32 v156, v156
	v_exp_f32_e32 v172, v172
	v_add_f32_e32 v157, v157, v180
	v_mfma_f32_32x32x16_bf16 v[80:95], v[244:247], v[160:163], v[80:95]
	v_add_f32_e32 v173, v173, v198
	v_exp_f32_e32 v157, v157
	v_exp_f32_e32 v173, v173
	v_add_f32_e32 v158, v158, v180
	v_add_f32_e32 v174, v174, v198
	v_exp_f32_e32 v158, v158
	v_exp_f32_e32 v174, v174
	ds_read_b64_tr_b16 v[244:245], v228 offset:4096
	ds_read_b64_tr_b16 v[246:247], v230 offset:4096
	v_mfma_f32_32x32x16_bf16 v[32:47], v[248:251], v[144:147], v[32:47]
	v_add_f32_e32 v159, v159, v180
	v_add_f32_e32 v175, v175, v198
	v_exp_f32_e32 v159, v159
	v_exp_f32_e32 v175, v175
	v_add_f32_e32 v215, v215, v152
	v_add_f32_e32 v217, v217, v168
	v_add_f32_e32 v215, v215, v153
	v_mfma_f32_32x32x16_bf16 v[48:63], v[248:251], v[160:163], v[48:63]
	v_add_f32_e32 v217, v217, v169
	v_add_f32_e32 v215, v215, v154
	v_add_f32_e32 v217, v217, v170
	v_add_f32_e32 v215, v215, v155
	v_add_f32_e32 v217, v217, v171
	v_add_f32_e32 v215, v215, v156
	v_add_f32_e32 v217, v217, v172
	v_mfma_f32_32x32x16_bf16 v[0:15], v[252:255], v[144:147], v[0:15]
	v_add_f32_e32 v215, v215, v157
	v_add_f32_e32 v217, v217, v173
	v_add_f32_e32 v215, v215, v158
	v_add_f32_e32 v217, v217, v174
	v_add_f32_e32 v215, v215, v159
	v_add_f32_e32 v217, v217, v175
	v_cvt_pk_bf16_f32 v152, v152, v153
	v_mfma_f32_32x32x16_bf16 v[16:31], v[252:255], v[160:163], v[16:31]
	v_cvt_pk_bf16_f32 v168, v168, v169
	v_cvt_pk_bf16_f32 v153, v154, v155
	v_cvt_pk_bf16_f32 v169, v170, v171
	v_cvt_pk_bf16_f32 v154, v156, v157
	v_cvt_pk_bf16_f32 v170, v172, v173
	v_cvt_pk_bf16_f32 v155, v158, v159
	v_cvt_pk_bf16_f32 v171, v174, v175
	v_add_f32_e32 v197, v197, v215
	v_add_f32_e32 v196, v196, v217
	s_waitcnt lgkmcnt(6)
	v_mfma_f32_32x32x16_bf16 v[112:127], v[148:151], v[152:155], v[112:127]
	v_mfma_f32_32x32x16_bf16 v[96:111], v[148:151], v[168:171], v[96:111]
	s_waitcnt lgkmcnt(4)
	v_mfma_f32_32x32x16_bf16 v[64:79], v[164:167], v[152:155], v[64:79]
	v_mfma_f32_32x32x16_bf16 v[80:95], v[164:167], v[168:171], v[80:95]
	s_waitcnt lgkmcnt(2)
	v_mfma_f32_32x32x16_bf16 v[32:47], v[202:205], v[152:155], v[32:47]
	v_mfma_f32_32x32x16_bf16 v[48:63], v[202:205], v[168:171], v[48:63]
	s_waitcnt lgkmcnt(0)
	v_mfma_f32_32x32x16_bf16 v[0:15], v[244:247], v[152:155], v[0:15]
	v_mfma_f32_32x32x16_bf16 v[16:31], v[244:247], v[168:171], v[16:31]
	s_add_i32 s78, s41, 1
	s_cmp_ge_u32 s78, s85
	s_cbranch_scc1 .LBB0_778

.LBB0_787:
	ds_read_b128 v[160:163], v237 offset:24576
	ds_read_b128 v[164:167], v189
	ds_read_b128 v[202:205], v235 offset:24576
	ds_read_b128 v[244:247], v189 offset:4096
	ds_read_b128 v[248:251], v236 offset:24576
	ds_read_b128 v[252:255], v189 offset:1024
	s_cmp_lg_u32 s66, s40
	s_waitcnt lgkmcnt(4)
	v_mfma_f32_32x32x16_bf16 v[144:159], v[160:163], v[164:167], v[128:143]
	s_waitcnt lgkmcnt(2)
	v_mfma_f32_32x32x16_bf16 v[160:175], v[202:205], v[244:247], v[128:143]
	ds_read_b128 v[202:205], v234 offset:24576
	ds_read_b128 v[244:247], v189 offset:5120
	s_waitcnt lgkmcnt(2)
	v_mfma_f32_32x32x16_bf16 v[144:159], v[248:251], v[252:255], v[144:159]
	ds_read_b128 v[248:251], v241 offset:24576
	ds_read_b128 v[252:255], v189 offset:2048
	s_waitcnt lgkmcnt(2)
	v_mfma_f32_32x32x16_bf16 v[160:175], v[202:205], v[244:247], v[160:175]
	ds_read_b128 v[202:205], v239 offset:24576
	ds_read_b128 v[244:247], v189 offset:6144
	s_waitcnt lgkmcnt(2)
	v_mfma_f32_32x32x16_bf16 v[144:159], v[248:251], v[252:255], v[144:159]
	ds_read_b128 v[248:251], v240 offset:24576
	ds_read_b128 v[252:255], v189 offset:3072
	s_waitcnt lgkmcnt(2)
	v_mfma_f32_32x32x16_bf16 v[160:175], v[202:205], v[244:247], v[160:175]
	ds_read_b128 v[202:205], v238 offset:24576
	ds_read_b128 v[244:247], v189 offset:7168
	s_waitcnt lgkmcnt(2)
	v_mfma_f32_32x32x16_bf16 v[144:159], v[248:251], v[252:255], v[144:159]
	s_waitcnt lgkmcnt(0)
	v_mfma_f32_32x32x16_bf16 v[160:175], v[202:205], v[244:247], v[160:175]
	ds_read_b64_tr_b16 v[202:203], v216 offset:24576
	ds_read_b64_tr_b16 v[204:205], v218 offset:24576
	ds_read_b64_tr_b16 v[244:245], v220 offset:24576
	ds_read_b64_tr_b16 v[246:247], v222 offset:24576
	ds_read_b64_tr_b16 v[248:249], v224 offset:24576
	ds_read_b64_tr_b16 v[250:251], v226 offset:24576
	ds_read_b64_tr_b16 v[252:253], v228 offset:24576
	ds_read_b64_tr_b16 v[254:255], v230 offset:24576
	s_cbranch_scc1 .Lat3_nomask
	s_nop 2
	v_cndmask_b32_e64 v180, v160, v242, s[2:3]
	v_cndmask_b32_e64 v198, v144, v242, s[2:3]
	v_cndmask_b32_e64 v161, v242, v161, s[4:5]
	v_cndmask_b32_e64 v160, v180, v160, s[4:5]
	v_cndmask_b32_e64 v145, v242, v145, s[4:5]
	v_cndmask_b32_e64 v144, v198, v144, s[4:5]
	v_cndmask_b32_e64 v162, v162, v242, s[6:7]
	v_cndmask_b32_e64 v146, v146, v242, s[6:7]
	v_cndmask_b32_e64 v163, v163, v242, s[8:9]
	v_cndmask_b32_e64 v147, v147, v242, s[8:9]
	v_cndmask_b32_e64 v164, v164, v242, s[10:11]
	v_cndmask_b32_e64 v148, v148, v242, s[10:11]
	v_cndmask_b32_e64 v165, v165, v242, s[12:13]
	v_cndmask_b32_e64 v149, v149, v242, s[12:13]
	v_cndmask_b32_e64 v166, v166, v242, s[14:15]
	v_cndmask_b32_e64 v150, v150, v242, s[14:15]
	v_cndmask_b32_e64 v167, v167, v242, s[16:17]
	v_cndmask_b32_e64 v151, v151, v242, s[16:17]
	v_cndmask_b32_e64 v168, v168, v242, s[18:19]
	v_cndmask_b32_e64 v152, v152, v242, s[18:19]
	v_cndmask_b32_e64 v169, v169, v242, s[20:21]
	v_cndmask_b32_e64 v153, v153, v242, s[20:21]
	v_cndmask_b32_e64 v170, v170, v242, s[22:23]
	v_cndmask_b32_e64 v154, v154, v242, s[22:23]
	v_cndmask_b32_e64 v171, v171, v242, s[24:25]
	v_cndmask_b32_e64 v155, v155, v242, s[24:25]
	v_cndmask_b32_e64 v172, v172, v242, s[26:27]
	v_cndmask_b32_e64 v156, v156, v242, s[26:27]
	v_cndmask_b32_e64 v173, v173, v242, s[28:29]
	v_cndmask_b32_e64 v157, v157, v242, s[28:29]
	v_cndmask_b32_e64 v174, v174, v242, s[30:31]
	v_cndmask_b32_e64 v158, v158, v242, s[30:31]
	v_cndmask_b32_e64 v175, v175, v242, s[34:35]
	v_cndmask_b32_e64 v159, v159, v242, s[34:35]
.Lat3_nomask:
	v_add_u32_e32 v215, s40, v185
	v_add_u32_e32 v215, 0xa0, v215
	v_cvt_f32_i32_e32 v215, v215
	v_mul_f32_e32 v200, v184, v215
	v_max_f32_e32 v217, v144, v145
	v_max_f32_e32 v219, v160, v161
	v_max3_f32 v217, v217, v146, v147
	v_max3_f32 v219, v219, v162, v163
	v_max3_f32 v217, v217, v148, v149
	v_max3_f32 v219, v219, v164, v165
	v_max3_f32 v217, v217, v150, v151
	v_max3_f32 v219, v219, v166, v167
	v_max3_f32 v217, v217, v152, v153
	v_max3_f32 v219, v219, v168, v169
	v_max3_f32 v217, v217, v154, v155
	v_max3_f32 v219, v219, v170, v171
	v_max3_f32 v217, v217, v156, v157
	v_max3_f32 v219, v219, v172, v173
	v_max3_f32 v217, v217, v158, v159
	v_max3_f32 v219, v219, v174, v175
	v_mov_b32_e32 v221, v217
	v_mov_b32_e32 v223, v219
	v_add_f32_e32 v227, 0x41000000, v199
	v_add_f32_e32 v215, 0x41000000, v201
	v_permlane32_swap_b32_e32 v217, v221
	v_permlane32_swap_b32_e32 v219, v223
	v_max_f32_e32 v217, v217, v221
	v_max_f32_e32 v219, v219, v223
	v_add_f32_e32 v225, v200, v217
	v_add_f32_e32 v229, v200, v219
	v_cmp_gt_f32_e32 vcc, v225, v227
	v_cmp_gt_f32_e64 s[0:1], v229, v215
	s_or_b64 vcc, vcc, s[0:1]
	s_cbranch_vccz .Lat3_noresc
	v_max_f32_e32 v217, v199, v225
	v_max_f32_e32 v219, v201, v229
	v_sub_f32_e32 v221, v199, v217
	v_exp_f32_e32 v180, v221
	v_sub_f32_e32 v221, v201, v219
	v_exp_f32_e32 v198, v221
	v_mov_b32_e32 v201, v219
	v_mul_f32_e32 v197, v197, v180
	v_mul_f32_e32 v196, v196, v198
	v_pk_mul_f32 v[112:113], v[112:113], v[180:181] op_sel_hi:[1,0]
	v_pk_mul_f32 v[114:115], v[114:115], v[180:181] op_sel_hi:[1,0]
	v_pk_mul_f32 v[116:117], v[116:117], v[180:181] op_sel_hi:[1,0]
	v_pk_mul_f32 v[118:119], v[118:119], v[180:181] op_sel_hi:[1,0]
	v_pk_mul_f32 v[120:121], v[120:121], v[180:181] op_sel_hi:[1,0]
	v_pk_mul_f32 v[122:123], v[122:123], v[180:181] op_sel_hi:[1,0]
	v_pk_mul_f32 v[124:125], v[124:125], v[180:181] op_sel_hi:[1,0]
	v_pk_mul_f32 v[126:127], v[126:127], v[180:181] op_sel_hi:[1,0]
	v_pk_mul_f32 v[64:65], v[64:65], v[180:181] op_sel_hi:[1,0]
	v_pk_mul_f32 v[66:67], v[66:67], v[180:181] op_sel_hi:[1,0]
	v_pk_mul_f32 v[68:69], v[68:69], v[180:181] op_sel_hi:[1,0]
	v_pk_mul_f32 v[70:71], v[70:71], v[180:181] op_sel_hi:[1,0]
	v_pk_mul_f32 v[72:73], v[72:73], v[180:181] op_sel_hi:[1,0]
	v_pk_mul_f32 v[74:75], v[74:75], v[180:181] op_sel_hi:[1,0]
	v_pk_mul_f32 v[76:77], v[76:77], v[180:181] op_sel_hi:[1,0]
	v_pk_mul_f32 v[78:79], v[78:79], v[180:181] op_sel_hi:[1,0]
	v_pk_mul_f32 v[32:33], v[32:33], v[180:181] op_sel_hi:[1,0]
	v_pk_mul_f32 v[34:35], v[34:35], v[180:181] op_sel_hi:[1,0]
	v_pk_mul_f32 v[36:37], v[36:37], v[180:181] op_sel_hi:[1,0]
	v_pk_mul_f32 v[38:39], v[38:39], v[180:181] op_sel_hi:[1,0]
	v_pk_mul_f32 v[40:41], v[40:41], v[180:181] op_sel_hi:[1,0]
	v_pk_mul_f32 v[42:43], v[42:43], v[180:181] op_sel_hi:[1,0]
	v_pk_mul_f32 v[44:45], v[44:45], v[180:181] op_sel_hi:[1,0]
	v_pk_mul_f32 v[46:47], v[46:47], v[180:181] op_sel_hi:[1,0]
	v_pk_mul_f32 v[0:1], v[0:1], v[180:181] op_sel_hi:[1,0]
	v_pk_mul_f32 v[2:3], v[2:3], v[180:181] op_sel_hi:[1,0]
	v_pk_mul_f32 v[4:5], v[4:5], v[180:181] op_sel_hi:[1,0]
	v_pk_mul_f32 v[6:7], v[6:7], v[180:181] op_sel_hi:[1,0]
	v_pk_mul_f32 v[8:9], v[8:9], v[180:181] op_sel_hi:[1,0]
	v_pk_mul_f32 v[10:11], v[10:11], v[180:181] op_sel_hi:[1,0]
	v_pk_mul_f32 v[12:13], v[12:13], v[180:181] op_sel_hi:[1,0]
	v_pk_mul_f32 v[14:15], v[14:15], v[180:181] op_sel_hi:[1,0]
	v_pk_mul_f32 v[96:97], v[96:97], v[198:199] op_sel_hi:[1,0]
	v_pk_mul_f32 v[98:99], v[98:99], v[198:199] op_sel_hi:[1,0]
	v_pk_mul_f32 v[100:101], v[100:101], v[198:199] op_sel_hi:[1,0]
	v_pk_mul_f32 v[102:103], v[102:103], v[198:199] op_sel_hi:[1,0]
	v_pk_mul_f32 v[104:105], v[104:105], v[198:199] op_sel_hi:[1,0]
	v_pk_mul_f32 v[106:107], v[106:107], v[198:199] op_sel_hi:[1,0]
	v_pk_mul_f32 v[108:109], v[108:109], v[198:199] op_sel_hi:[1,0]
	v_pk_mul_f32 v[110:111], v[110:111], v[198:199] op_sel_hi:[1,0]
	v_pk_mul_f32 v[80:81], v[80:81], v[198:199] op_sel_hi:[1,0]
	v_pk_mul_f32 v[82:83], v[82:83], v[198:199] op_sel_hi:[1,0]
	v_pk_mul_f32 v[84:85], v[84:85], v[198:199] op_sel_hi:[1,0]
	v_pk_mul_f32 v[86:87], v[86:87], v[198:199] op_sel_hi:[1,0]
	v_pk_mul_f32 v[88:89], v[88:89], v[198:199] op_sel_hi:[1,0]
	v_pk_mul_f32 v[90:91], v[90:91], v[198:199] op_sel_hi:[1,0]
	v_pk_mul_f32 v[92:93], v[92:93], v[198:199] op_sel_hi:[1,0]
	v_pk_mul_f32 v[94:95], v[94:95], v[198:199] op_sel_hi:[1,0]
	v_pk_mul_f32 v[48:49], v[48:49], v[198:199] op_sel_hi:[1,0]
	v_pk_mul_f32 v[50:51], v[50:51], v[198:199] op_sel_hi:[1,0]
	v_pk_mul_f32 v[52:53], v[52:53], v[198:199] op_sel_hi:[1,0]
	v_pk_mul_f32 v[54:55], v[54:55], v[198:199] op_sel_hi:[1,0]
	v_pk_mul_f32 v[56:57], v[56:57], v[198:199] op_sel_hi:[1,0]
	v_pk_mul_f32 v[58:59], v[58:59], v[198:199] op_sel_hi:[1,0]
	v_pk_mul_f32 v[60:61], v[60:61], v[198:199] op_sel_hi:[1,0]
	v_pk_mul_f32 v[62:63], v[62:63], v[198:199] op_sel_hi:[1,0]
	v_pk_mul_f32 v[16:17], v[16:17], v[198:199] op_sel_hi:[1,0]
	v_pk_mul_f32 v[18:19], v[18:19], v[198:199] op_sel_hi:[1,0]
	v_pk_mul_f32 v[20:21], v[20:21], v[198:199] op_sel_hi:[1,0]
	v_pk_mul_f32 v[22:23], v[22:23], v[198:199] op_sel_hi:[1,0]
	v_pk_mul_f32 v[24:25], v[24:25], v[198:199] op_sel_hi:[1,0]
	v_pk_mul_f32 v[26:27], v[26:27], v[198:199] op_sel_hi:[1,0]
	v_pk_mul_f32 v[28:29], v[28:29], v[198:199] op_sel_hi:[1,0]
	v_pk_mul_f32 v[30:31], v[30:31], v[198:199] op_sel_hi:[1,0]
	v_mov_b32_e32 v199, v217
.Lat3_noresc:
	v_sub_f32_e32 v180, v200, v199
	v_sub_f32_e32 v198, v200, v201
	v_add_f32_e32 v144, v144, v180
	v_add_f32_e32 v160, v160, v198
	v_exp_f32_e32 v144, v144
	v_exp_f32_e32 v160, v160
	v_add_f32_e32 v145, v145, v180
	v_add_f32_e32 v161, v161, v198
	v_exp_f32_e32 v145, v145
	v_exp_f32_e32 v161, v161
	v_add_f32_e32 v146, v146, v180
	v_add_f32_e32 v162, v162, v198
	v_exp_f32_e32 v146, v146
	v_exp_f32_e32 v162, v162
	v_add_f32_e32 v147, v147, v180
	v_add_f32_e32 v163, v163, v198
	v_exp_f32_e32 v147, v147
	v_exp_f32_e32 v163, v163
	v_add_f32_e32 v148, v148, v180
	v_add_f32_e32 v164, v164, v198
	v_exp_f32_e32 v148, v148
	v_exp_f32_e32 v164, v164
	v_add_f32_e32 v149, v149, v180
	v_add_f32_e32 v165, v165, v198
	v_exp_f32_e32 v149, v149
	v_exp_f32_e32 v165, v165
	v_add_f32_e32 v150, v150, v180
	v_add_f32_e32 v166, v166, v198
	v_exp_f32_e32 v150, v150
	v_exp_f32_e32 v166, v166
	v_add_f32_e32 v151, v151, v180
	v_add_f32_e32 v167, v167, v198
	v_exp_f32_e32 v151, v151
	v_exp_f32_e32 v167, v167
	v_add_f32_e32 v215, v144, v145
	v_add_f32_e32 v217, v160, v161
	v_add_f32_e32 v215, v215, v146
	v_add_f32_e32 v217, v217, v162
	v_add_f32_e32 v215, v215, v147
	v_add_f32_e32 v217, v217, v163
	v_add_f32_e32 v215, v215, v148
	v_add_f32_e32 v217, v217, v164
	v_add_f32_e32 v215, v215, v149
	v_add_f32_e32 v217, v217, v165
	v_add_f32_e32 v215, v215, v150
	v_add_f32_e32 v217, v217, v166
	v_add_f32_e32 v215, v215, v151
	v_add_f32_e32 v217, v217, v167
	v_cvt_pk_bf16_f32 v144, v144, v145
	v_cvt_pk_bf16_f32 v160, v160, v161
	v_cvt_pk_bf16_f32 v145, v146, v147
	v_cvt_pk_bf16_f32 v161, v162, v163
	v_cvt_pk_bf16_f32 v146, v148, v149
	v_cvt_pk_bf16_f32 v162, v164, v165
	v_cvt_pk_bf16_f32 v147, v150, v151
	v_cvt_pk_bf16_f32 v163, v166, v167
	ds_read_b64_tr_b16 v[148:149], v216 offset:28672
	ds_read_b64_tr_b16 v[150:151], v218 offset:28672
	ds_read_b64_tr_b16 v[164:165], v220 offset:28672
	ds_read_b64_tr_b16 v[166:167], v222 offset:28672
	s_waitcnt lgkmcnt(4)
	v_mfma_f32_32x32x16_bf16 v[112:127], v[202:205], v[144:147], v[112:127]
	v_add_f32_e32 v152, v152, v180
	v_add_f32_e32 v168, v168, v198
	v_exp_f32_e32 v152, v152
	v_exp_f32_e32 v168, v168
	v_add_f32_e32 v153, v153, v180
	v_add_f32_e32 v169, v169, v198
	v_exp_f32_e32 v153, v153
	v_mfma_f32_32x32x16_bf16 v[96:111], v[202:205], v[160:163], v[96:111]
	v_exp_f32_e32 v169, v169
	v_add_f32_e32 v154, v154, v180
	v_add_f32_e32 v170, v170, v198
	v_exp_f32_e32 v154, v154
	v_exp_f32_e32 v170, v170
	v_add_f32_e32 v155, v155, v180
	v_add_f32_e32 v171, v171, v198
	ds_read_b64_tr_b16 v[202:203], v224 offset:28672
	ds_read_b64_tr_b16 v[204:205], v226 offset:28672
	v_mfma_f32_32x32x16_bf16 v[64:79], v[244:247], v[144:147], v[64:79]
	v_exp_f32_e32 v155, v155
	v_exp_f32_e32 v171, v171
	v_add_f32_e32 v156, v156, v180
	v_add_f32_e32 v172, v172, v198
	v_exp_f32_e32 v156, v156
	v_exp_f32_e32 v172, v172
	v_add_f32_e32 v157, v157, v180
	v_mfma_f32_32x32x16_bf16 v[80:95], v[244:247], v[160:163], v[80:95]
	v_add_f32_e32 v173, v173, v198
	v_exp_f32_e32 v157, v157
	v_exp_f32_e32 v173, v173
	v_add_f32_e32 v158, v158, v180
	v_add_f32_e32 v174, v174, v198
	v_exp_f32_e32 v158, v158
	v_exp_f32_e32 v174, v174
	ds_read_b64_tr_b16 v[244:245], v228 offset:28672
	ds_read_b64_tr_b16 v[246:247], v230 offset:28672
	v_mfma_f32_32x32x16_bf16 v[32:47], v[248:251], v[144:147], v[32:47]
	v_add_f32_e32 v159, v159, v180
	v_add_f32_e32 v175, v175, v198
	v_exp_f32_e32 v159, v159
	v_exp_f32_e32 v175, v175
	v_add_f32_e32 v215, v215, v152
	v_add_f32_e32 v217, v217, v168
	v_add_f32_e32 v215, v215, v153
	v_mfma_f32_32x32x16_bf16 v[48:63], v[248:251], v[160:163], v[48:63]
	v_add_f32_e32 v217, v217, v169
	v_add_f32_e32 v215, v215, v154
	v_add_f32_e32 v217, v217, v170
	v_add_f32_e32 v215, v215, v155
	v_add_f32_e32 v217, v217, v171
	v_add_f32_e32 v215, v215, v156
	v_add_f32_e32 v217, v217, v172
	v_mfma_f32_32x32x16_bf16 v[0:15], v[252:255], v[144:147], v[0:15]
	v_add_f32_e32 v215, v215, v157
	v_add_f32_e32 v217, v217, v173
	v_add_f32_e32 v215, v215, v158
	v_add_f32_e32 v217, v217, v174
	v_add_f32_e32 v215, v215, v159
	v_add_f32_e32 v217, v217, v175
	v_cvt_pk_bf16_f32 v152, v152, v153
	v_mfma_f32_32x32x16_bf16 v[16:31], v[252:255], v[160:163], v[16:31]
	v_cvt_pk_bf16_f32 v168, v168, v169
	v_cvt_pk_bf16_f32 v153, v154, v155
	v_cvt_pk_bf16_f32 v169, v170, v171
	v_cvt_pk_bf16_f32 v154, v156, v157
	v_cvt_pk_bf16_f32 v170, v172, v173
	v_cvt_pk_bf16_f32 v155, v158, v159
	v_cvt_pk_bf16_f32 v171, v174, v175
	v_add_f32_e32 v197, v197, v215
	v_add_f32_e32 v196, v196, v217
	s_waitcnt lgkmcnt(6)
	v_mfma_f32_32x32x16_bf16 v[112:127], v[148:151], v[152:155], v[112:127]
	v_mfma_f32_32x32x16_bf16 v[96:111], v[148:151], v[168:171], v[96:111]
	s_waitcnt lgkmcnt(4)
	v_mfma_f32_32x32x16_bf16 v[64:79], v[164:167], v[152:155], v[64:79]
	v_mfma_f32_32x32x16_bf16 v[80:95], v[164:167], v[168:171], v[80:95]
	s_waitcnt lgkmcnt(2)
	v_mfma_f32_32x32x16_bf16 v[32:47], v[202:205], v[152:155], v[32:47]
	v_mfma_f32_32x32x16_bf16 v[48:63], v[202:205], v[168:171], v[48:63]
	s_waitcnt lgkmcnt(0)
	v_mfma_f32_32x32x16_bf16 v[0:15], v[244:247], v[152:155], v[0:15]
	v_mfma_f32_32x32x16_bf16 v[16:31], v[244:247], v[168:171], v[16:31]
	s_cmp_gt_i32 s78, s84
	s_cbranch_scc1 .LBB0_778
.LBB0_792:
	ds_read_b128 v[160:163], v237 offset:16384
	ds_read_b128 v[164:167], v189
	ds_read_b128 v[202:205], v235 offset:16384
	ds_read_b128 v[244:247], v189 offset:4096
	ds_read_b128 v[248:251], v236 offset:16384
	ds_read_b128 v[252:255], v189 offset:1024
	s_cmp_lg_u32 s39, s40
	s_waitcnt lgkmcnt(4)
	v_mfma_f32_32x32x16_bf16 v[144:159], v[160:163], v[164:167], v[128:143]
	s_waitcnt lgkmcnt(2)
	v_mfma_f32_32x32x16_bf16 v[160:175], v[202:205], v[244:247], v[128:143]
	ds_read_b128 v[202:205], v234 offset:16384
	ds_read_b128 v[244:247], v189 offset:5120
	s_waitcnt lgkmcnt(2)
	v_mfma_f32_32x32x16_bf16 v[144:159], v[248:251], v[252:255], v[144:159]
	ds_read_b128 v[248:251], v241 offset:16384
	ds_read_b128 v[252:255], v189 offset:2048
	s_waitcnt lgkmcnt(2)
	v_mfma_f32_32x32x16_bf16 v[160:175], v[202:205], v[244:247], v[160:175]
	ds_read_b128 v[202:205], v239 offset:16384
	ds_read_b128 v[244:247], v189 offset:6144
	s_waitcnt lgkmcnt(2)
	v_mfma_f32_32x32x16_bf16 v[144:159], v[248:251], v[252:255], v[144:159]
	ds_read_b128 v[248:251], v240 offset:16384
	ds_read_b128 v[252:255], v189 offset:3072
	s_waitcnt lgkmcnt(2)
	v_mfma_f32_32x32x16_bf16 v[160:175], v[202:205], v[244:247], v[160:175]
	ds_read_b128 v[202:205], v238 offset:16384
	ds_read_b128 v[244:247], v189 offset:7168
	s_waitcnt lgkmcnt(2)
	v_mfma_f32_32x32x16_bf16 v[144:159], v[248:251], v[252:255], v[144:159]
	s_waitcnt lgkmcnt(0)
	v_mfma_f32_32x32x16_bf16 v[160:175], v[202:205], v[244:247], v[160:175]
	ds_read_b64_tr_b16 v[202:203], v216 offset:16384
	ds_read_b64_tr_b16 v[204:205], v218 offset:16384
	ds_read_b64_tr_b16 v[244:245], v220 offset:16384
	ds_read_b64_tr_b16 v[246:247], v222 offset:16384
	ds_read_b64_tr_b16 v[248:249], v224 offset:16384
	ds_read_b64_tr_b16 v[250:251], v226 offset:16384
	ds_read_b64_tr_b16 v[252:253], v228 offset:16384
	ds_read_b64_tr_b16 v[254:255], v230 offset:16384
	s_cbranch_scc1 .Lat4_nomask
	s_nop 2
	v_cndmask_b32_e64 v180, v160, v242, s[2:3]
	v_cndmask_b32_e64 v198, v144, v242, s[2:3]
	v_cndmask_b32_e64 v161, v242, v161, s[4:5]
	v_cndmask_b32_e64 v160, v180, v160, s[4:5]
	v_cndmask_b32_e64 v145, v242, v145, s[4:5]
	v_cndmask_b32_e64 v144, v198, v144, s[4:5]
	v_cndmask_b32_e64 v162, v162, v242, s[6:7]
	v_cndmask_b32_e64 v146, v146, v242, s[6:7]
	v_cndmask_b32_e64 v163, v163, v242, s[8:9]
	v_cndmask_b32_e64 v147, v147, v242, s[8:9]
	v_cndmask_b32_e64 v164, v164, v242, s[10:11]
	v_cndmask_b32_e64 v148, v148, v242, s[10:11]
	v_cndmask_b32_e64 v165, v165, v242, s[12:13]
	v_cndmask_b32_e64 v149, v149, v242, s[12:13]
	v_cndmask_b32_e64 v166, v166, v242, s[14:15]
	v_cndmask_b32_e64 v150, v150, v242, s[14:15]
	v_cndmask_b32_e64 v167, v167, v242, s[16:17]
	v_cndmask_b32_e64 v151, v151, v242, s[16:17]
	v_cndmask_b32_e64 v168, v168, v242, s[18:19]
	v_cndmask_b32_e64 v152, v152, v242, s[18:19]
	v_cndmask_b32_e64 v169, v169, v242, s[20:21]
	v_cndmask_b32_e64 v153, v153, v242, s[20:21]
	v_cndmask_b32_e64 v170, v170, v242, s[22:23]
	v_cndmask_b32_e64 v154, v154, v242, s[22:23]
	v_cndmask_b32_e64 v171, v171, v242, s[24:25]
	v_cndmask_b32_e64 v155, v155, v242, s[24:25]
	v_cndmask_b32_e64 v172, v172, v242, s[26:27]
	v_cndmask_b32_e64 v156, v156, v242, s[26:27]
	v_cndmask_b32_e64 v173, v173, v242, s[28:29]
	v_cndmask_b32_e64 v157, v157, v242, s[28:29]
	v_cndmask_b32_e64 v174, v174, v242, s[30:31]
	v_cndmask_b32_e64 v158, v158, v242, s[30:31]
	v_cndmask_b32_e64 v175, v175, v242, s[34:35]
	v_cndmask_b32_e64 v159, v159, v242, s[34:35]
.Lat4_nomask:
	v_add_u32_e32 v215, s40, v185
	v_add_u32_e32 v215, 0x80, v215
	v_cvt_f32_i32_e32 v215, v215
	v_mul_f32_e32 v200, v184, v215
	v_max_f32_e32 v217, v144, v145
	v_max_f32_e32 v219, v160, v161
	v_max3_f32 v217, v217, v146, v147
	v_max3_f32 v219, v219, v162, v163
	v_max3_f32 v217, v217, v148, v149
	v_max3_f32 v219, v219, v164, v165
	v_max3_f32 v217, v217, v150, v151
	v_max3_f32 v219, v219, v166, v167
	v_max3_f32 v217, v217, v152, v153
	v_max3_f32 v219, v219, v168, v169
	v_max3_f32 v217, v217, v154, v155
	v_max3_f32 v219, v219, v170, v171
	v_max3_f32 v217, v217, v156, v157
	v_max3_f32 v219, v219, v172, v173
	v_max3_f32 v217, v217, v158, v159
	v_max3_f32 v219, v219, v174, v175
	v_mov_b32_e32 v221, v217
	v_mov_b32_e32 v223, v219
	v_add_f32_e32 v227, 0x41000000, v199
	v_add_f32_e32 v215, 0x41000000, v201
	v_permlane32_swap_b32_e32 v217, v221
	v_permlane32_swap_b32_e32 v219, v223
	v_max_f32_e32 v217, v217, v221
	v_max_f32_e32 v219, v219, v223
	v_add_f32_e32 v225, v200, v217
	v_add_f32_e32 v229, v200, v219
	v_cmp_gt_f32_e32 vcc, v225, v227
	v_cmp_gt_f32_e64 s[0:1], v229, v215
	s_or_b64 vcc, vcc, s[0:1]
	s_cbranch_vccz .Lat4_noresc
	v_max_f32_e32 v217, v199, v225
	v_max_f32_e32 v219, v201, v229
	v_sub_f32_e32 v221, v199, v217
	v_exp_f32_e32 v180, v221
	v_sub_f32_e32 v221, v201, v219
	v_exp_f32_e32 v198, v221
	v_mov_b32_e32 v201, v219
	v_mul_f32_e32 v197, v197, v180
	v_mul_f32_e32 v196, v196, v198
	v_pk_mul_f32 v[112:113], v[112:113], v[180:181] op_sel_hi:[1,0]
	v_pk_mul_f32 v[114:115], v[114:115], v[180:181] op_sel_hi:[1,0]
	v_pk_mul_f32 v[116:117], v[116:117], v[180:181] op_sel_hi:[1,0]
	v_pk_mul_f32 v[118:119], v[118:119], v[180:181] op_sel_hi:[1,0]
	v_pk_mul_f32 v[120:121], v[120:121], v[180:181] op_sel_hi:[1,0]
	v_pk_mul_f32 v[122:123], v[122:123], v[180:181] op_sel_hi:[1,0]
	v_pk_mul_f32 v[124:125], v[124:125], v[180:181] op_sel_hi:[1,0]
	v_pk_mul_f32 v[126:127], v[126:127], v[180:181] op_sel_hi:[1,0]
	v_pk_mul_f32 v[64:65], v[64:65], v[180:181] op_sel_hi:[1,0]
	v_pk_mul_f32 v[66:67], v[66:67], v[180:181] op_sel_hi:[1,0]
	v_pk_mul_f32 v[68:69], v[68:69], v[180:181] op_sel_hi:[1,0]
	v_pk_mul_f32 v[70:71], v[70:71], v[180:181] op_sel_hi:[1,0]
	v_pk_mul_f32 v[72:73], v[72:73], v[180:181] op_sel_hi:[1,0]
	v_pk_mul_f32 v[74:75], v[74:75], v[180:181] op_sel_hi:[1,0]
	v_pk_mul_f32 v[76:77], v[76:77], v[180:181] op_sel_hi:[1,0]
	v_pk_mul_f32 v[78:79], v[78:79], v[180:181] op_sel_hi:[1,0]
	v_pk_mul_f32 v[32:33], v[32:33], v[180:181] op_sel_hi:[1,0]
	v_pk_mul_f32 v[34:35], v[34:35], v[180:181] op_sel_hi:[1,0]
	v_pk_mul_f32 v[36:37], v[36:37], v[180:181] op_sel_hi:[1,0]
	v_pk_mul_f32 v[38:39], v[38:39], v[180:181] op_sel_hi:[1,0]
	v_pk_mul_f32 v[40:41], v[40:41], v[180:181] op_sel_hi:[1,0]
	v_pk_mul_f32 v[42:43], v[42:43], v[180:181] op_sel_hi:[1,0]
	v_pk_mul_f32 v[44:45], v[44:45], v[180:181] op_sel_hi:[1,0]
	v_pk_mul_f32 v[46:47], v[46:47], v[180:181] op_sel_hi:[1,0]
	v_pk_mul_f32 v[0:1], v[0:1], v[180:181] op_sel_hi:[1,0]
	v_pk_mul_f32 v[2:3], v[2:3], v[180:181] op_sel_hi:[1,0]
	v_pk_mul_f32 v[4:5], v[4:5], v[180:181] op_sel_hi:[1,0]
	v_pk_mul_f32 v[6:7], v[6:7], v[180:181] op_sel_hi:[1,0]
	v_pk_mul_f32 v[8:9], v[8:9], v[180:181] op_sel_hi:[1,0]
	v_pk_mul_f32 v[10:11], v[10:11], v[180:181] op_sel_hi:[1,0]
	v_pk_mul_f32 v[12:13], v[12:13], v[180:181] op_sel_hi:[1,0]
	v_pk_mul_f32 v[14:15], v[14:15], v[180:181] op_sel_hi:[1,0]
	v_pk_mul_f32 v[96:97], v[96:97], v[198:199] op_sel_hi:[1,0]
	v_pk_mul_f32 v[98:99], v[98:99], v[198:199] op_sel_hi:[1,0]
	v_pk_mul_f32 v[100:101], v[100:101], v[198:199] op_sel_hi:[1,0]
	v_pk_mul_f32 v[102:103], v[102:103], v[198:199] op_sel_hi:[1,0]
	v_pk_mul_f32 v[104:105], v[104:105], v[198:199] op_sel_hi:[1,0]
	v_pk_mul_f32 v[106:107], v[106:107], v[198:199] op_sel_hi:[1,0]
	v_pk_mul_f32 v[108:109], v[108:109], v[198:199] op_sel_hi:[1,0]
	v_pk_mul_f32 v[110:111], v[110:111], v[198:199] op_sel_hi:[1,0]
	v_pk_mul_f32 v[80:81], v[80:81], v[198:199] op_sel_hi:[1,0]
	v_pk_mul_f32 v[82:83], v[82:83], v[198:199] op_sel_hi:[1,0]
	v_pk_mul_f32 v[84:85], v[84:85], v[198:199] op_sel_hi:[1,0]
	v_pk_mul_f32 v[86:87], v[86:87], v[198:199] op_sel_hi:[1,0]
	v_pk_mul_f32 v[88:89], v[88:89], v[198:199] op_sel_hi:[1,0]
	v_pk_mul_f32 v[90:91], v[90:91], v[198:199] op_sel_hi:[1,0]
	v_pk_mul_f32 v[92:93], v[92:93], v[198:199] op_sel_hi:[1,0]
	v_pk_mul_f32 v[94:95], v[94:95], v[198:199] op_sel_hi:[1,0]
	v_pk_mul_f32 v[48:49], v[48:49], v[198:199] op_sel_hi:[1,0]
	v_pk_mul_f32 v[50:51], v[50:51], v[198:199] op_sel_hi:[1,0]
	v_pk_mul_f32 v[52:53], v[52:53], v[198:199] op_sel_hi:[1,0]
	v_pk_mul_f32 v[54:55], v[54:55], v[198:199] op_sel_hi:[1,0]
	v_pk_mul_f32 v[56:57], v[56:57], v[198:199] op_sel_hi:[1,0]
	v_pk_mul_f32 v[58:59], v[58:59], v[198:199] op_sel_hi:[1,0]
	v_pk_mul_f32 v[60:61], v[60:61], v[198:199] op_sel_hi:[1,0]
	v_pk_mul_f32 v[62:63], v[62:63], v[198:199] op_sel_hi:[1,0]
	v_pk_mul_f32 v[16:17], v[16:17], v[198:199] op_sel_hi:[1,0]
	v_pk_mul_f32 v[18:19], v[18:19], v[198:199] op_sel_hi:[1,0]
	v_pk_mul_f32 v[20:21], v[20:21], v[198:199] op_sel_hi:[1,0]
	v_pk_mul_f32 v[22:23], v[22:23], v[198:199] op_sel_hi:[1,0]
	v_pk_mul_f32 v[24:25], v[24:25], v[198:199] op_sel_hi:[1,0]
	v_pk_mul_f32 v[26:27], v[26:27], v[198:199] op_sel_hi:[1,0]
	v_pk_mul_f32 v[28:29], v[28:29], v[198:199] op_sel_hi:[1,0]
	v_pk_mul_f32 v[30:31], v[30:31], v[198:199] op_sel_hi:[1,0]
	v_mov_b32_e32 v199, v217
.Lat4_noresc:
	v_sub_f32_e32 v180, v200, v199
	v_sub_f32_e32 v198, v200, v201
	v_add_f32_e32 v144, v144, v180
	v_add_f32_e32 v160, v160, v198
	v_exp_f32_e32 v144, v144
	v_exp_f32_e32 v160, v160
	v_add_f32_e32 v145, v145, v180
	v_add_f32_e32 v161, v161, v198
	v_exp_f32_e32 v145, v145
	v_exp_f32_e32 v161, v161
	v_add_f32_e32 v146, v146, v180
	v_add_f32_e32 v162, v162, v198
	v_exp_f32_e32 v146, v146
	v_exp_f32_e32 v162, v162
	v_add_f32_e32 v147, v147, v180
	v_add_f32_e32 v163, v163, v198
	v_exp_f32_e32 v147, v147
	v_exp_f32_e32 v163, v163
	v_add_f32_e32 v148, v148, v180
	v_add_f32_e32 v164, v164, v198
	v_exp_f32_e32 v148, v148
	v_exp_f32_e32 v164, v164
	v_add_f32_e32 v149, v149, v180
	v_add_f32_e32 v165, v165, v198
	v_exp_f32_e32 v149, v149
	v_exp_f32_e32 v165, v165
	v_add_f32_e32 v150, v150, v180
	v_add_f32_e32 v166, v166, v198
	v_exp_f32_e32 v150, v150
	v_exp_f32_e32 v166, v166
	v_add_f32_e32 v151, v151, v180
	v_add_f32_e32 v167, v167, v198
	v_exp_f32_e32 v151, v151
	v_exp_f32_e32 v167, v167
	v_add_f32_e32 v215, v144, v145
	v_add_f32_e32 v217, v160, v161
	v_add_f32_e32 v215, v215, v146
	v_add_f32_e32 v217, v217, v162
	v_add_f32_e32 v215, v215, v147
	v_add_f32_e32 v217, v217, v163
	v_add_f32_e32 v215, v215, v148
	v_add_f32_e32 v217, v217, v164
	v_add_f32_e32 v215, v215, v149
	v_add_f32_e32 v217, v217, v165
	v_add_f32_e32 v215, v215, v150
	v_add_f32_e32 v217, v217, v166
	v_add_f32_e32 v215, v215, v151
	v_add_f32_e32 v217, v217, v167
	v_cvt_pk_bf16_f32 v144, v144, v145
	v_cvt_pk_bf16_f32 v160, v160, v161
	v_cvt_pk_bf16_f32 v145, v146, v147
	v_cvt_pk_bf16_f32 v161, v162, v163
	v_cvt_pk_bf16_f32 v146, v148, v149
	v_cvt_pk_bf16_f32 v162, v164, v165
	v_cvt_pk_bf16_f32 v147, v150, v151
	v_cvt_pk_bf16_f32 v163, v166, v167
	ds_read_b64_tr_b16 v[148:149], v216 offset:20480
	ds_read_b64_tr_b16 v[150:151], v218 offset:20480
	ds_read_b64_tr_b16 v[164:165], v220 offset:20480
	ds_read_b64_tr_b16 v[166:167], v222 offset:20480
	s_waitcnt lgkmcnt(4)
	v_mfma_f32_32x32x16_bf16 v[112:127], v[202:205], v[144:147], v[112:127]
	v_add_f32_e32 v152, v152, v180
	v_add_f32_e32 v168, v168, v198
	v_exp_f32_e32 v152, v152
	v_exp_f32_e32 v168, v168
	v_add_f32_e32 v153, v153, v180
	v_add_f32_e32 v169, v169, v198
	v_exp_f32_e32 v153, v153
	v_mfma_f32_32x32x16_bf16 v[96:111], v[202:205], v[160:163], v[96:111]
	v_exp_f32_e32 v169, v169
	v_add_f32_e32 v154, v154, v180
	v_add_f32_e32 v170, v170, v198
	v_exp_f32_e32 v154, v154
	v_exp_f32_e32 v170, v170
	v_add_f32_e32 v155, v155, v180
	v_add_f32_e32 v171, v171, v198
	ds_read_b64_tr_b16 v[202:203], v224 offset:20480
	ds_read_b64_tr_b16 v[204:205], v226 offset:20480
	v_mfma_f32_32x32x16_bf16 v[64:79], v[244:247], v[144:147], v[64:79]
	v_exp_f32_e32 v155, v155
	v_exp_f32_e32 v171, v171
	v_add_f32_e32 v156, v156, v180
	v_add_f32_e32 v172, v172, v198
	v_exp_f32_e32 v156, v156
	v_exp_f32_e32 v172, v172
	v_add_f32_e32 v157, v157, v180
	v_mfma_f32_32x32x16_bf16 v[80:95], v[244:247], v[160:163], v[80:95]
	v_add_f32_e32 v173, v173, v198
	v_exp_f32_e32 v157, v157
	v_exp_f32_e32 v173, v173
	v_add_f32_e32 v158, v158, v180
	v_add_f32_e32 v174, v174, v198
	v_exp_f32_e32 v158, v158
	v_exp_f32_e32 v174, v174
	ds_read_b64_tr_b16 v[244:245], v228 offset:20480
	ds_read_b64_tr_b16 v[246:247], v230 offset:20480
	v_mfma_f32_32x32x16_bf16 v[32:47], v[248:251], v[144:147], v[32:47]
	v_add_f32_e32 v159, v159, v180
	v_add_f32_e32 v175, v175, v198
	v_exp_f32_e32 v159, v159
	v_exp_f32_e32 v175, v175
	v_add_f32_e32 v215, v215, v152
	v_add_f32_e32 v217, v217, v168
	v_add_f32_e32 v215, v215, v153
	v_mfma_f32_32x32x16_bf16 v[48:63], v[248:251], v[160:163], v[48:63]
	v_add_f32_e32 v217, v217, v169
	v_add_f32_e32 v215, v215, v154
	v_add_f32_e32 v217, v217, v170
	v_add_f32_e32 v215, v215, v155
	v_add_f32_e32 v217, v217, v171
	v_add_f32_e32 v215, v215, v156
	v_add_f32_e32 v217, v217, v172
	v_mfma_f32_32x32x16_bf16 v[0:15], v[252:255], v[144:147], v[0:15]
	v_add_f32_e32 v215, v215, v157
	v_add_f32_e32 v217, v217, v173
	v_add_f32_e32 v215, v215, v158
	v_add_f32_e32 v217, v217, v174
	v_add_f32_e32 v215, v215, v159
	v_add_f32_e32 v217, v217, v175
	v_cvt_pk_bf16_f32 v152, v152, v153
	v_mfma_f32_32x32x16_bf16 v[16:31], v[252:255], v[160:163], v[16:31]
	v_cvt_pk_bf16_f32 v168, v168, v169
	v_cvt_pk_bf16_f32 v153, v154, v155
	v_cvt_pk_bf16_f32 v169, v170, v171
	v_cvt_pk_bf16_f32 v154, v156, v157
	v_cvt_pk_bf16_f32 v170, v172, v173
	v_cvt_pk_bf16_f32 v155, v158, v159
	v_cvt_pk_bf16_f32 v171, v174, v175
	v_add_f32_e32 v197, v197, v215
	v_add_f32_e32 v196, v196, v217
	s_waitcnt lgkmcnt(6)
	v_mfma_f32_32x32x16_bf16 v[112:127], v[148:151], v[152:155], v[112:127]
	v_mfma_f32_32x32x16_bf16 v[96:111], v[148:151], v[168:171], v[96:111]
	s_waitcnt lgkmcnt(4)
	v_mfma_f32_32x32x16_bf16 v[64:79], v[164:167], v[152:155], v[64:79]
	v_mfma_f32_32x32x16_bf16 v[80:95], v[164:167], v[168:171], v[80:95]
	s_waitcnt lgkmcnt(2)
	v_mfma_f32_32x32x16_bf16 v[32:47], v[202:205], v[152:155], v[32:47]
	v_mfma_f32_32x32x16_bf16 v[48:63], v[202:205], v[168:171], v[48:63]
	s_waitcnt lgkmcnt(0)
	v_mfma_f32_32x32x16_bf16 v[0:15], v[244:247], v[152:155], v[0:15]
	v_mfma_f32_32x32x16_bf16 v[16:31], v[244:247], v[168:171], v[16:31]
	s_add_i32 s0, s41, 2
	s_cmp_ge_u32 s0, s85
	s_cbranch_scc1 .LBB0_753
	s_branch .LBB0_779

.LBB0_800:
	ds_read_b128 v[160:163], v237 offset:40960
	ds_read_b128 v[164:167], v189
	ds_read_b128 v[202:205], v235 offset:40960
	ds_read_b128 v[244:247], v189 offset:4096
	ds_read_b128 v[248:251], v236 offset:40960
	ds_read_b128 v[252:255], v189 offset:1024
	s_cmp_lg_u32 s65, s40
	s_waitcnt lgkmcnt(4)
	v_mfma_f32_32x32x16_bf16 v[144:159], v[160:163], v[164:167], v[128:143]
	s_waitcnt lgkmcnt(2)
	v_mfma_f32_32x32x16_bf16 v[160:175], v[202:205], v[244:247], v[128:143]
	ds_read_b128 v[202:205], v234 offset:40960
	ds_read_b128 v[244:247], v189 offset:5120
	s_waitcnt lgkmcnt(2)
	v_mfma_f32_32x32x16_bf16 v[144:159], v[248:251], v[252:255], v[144:159]
	ds_read_b128 v[248:251], v241 offset:40960
	ds_read_b128 v[252:255], v189 offset:2048
	s_waitcnt lgkmcnt(2)
	v_mfma_f32_32x32x16_bf16 v[160:175], v[202:205], v[244:247], v[160:175]
	ds_read_b128 v[202:205], v239 offset:40960
	ds_read_b128 v[244:247], v189 offset:6144
	s_waitcnt lgkmcnt(2)
	v_mfma_f32_32x32x16_bf16 v[144:159], v[248:251], v[252:255], v[144:159]
	ds_read_b128 v[248:251], v240 offset:40960
	ds_read_b128 v[252:255], v189 offset:3072
	s_waitcnt lgkmcnt(2)
	v_mfma_f32_32x32x16_bf16 v[160:175], v[202:205], v[244:247], v[160:175]
	ds_read_b128 v[202:205], v238 offset:40960
	ds_read_b128 v[244:247], v189 offset:7168
	s_waitcnt lgkmcnt(2)
	v_mfma_f32_32x32x16_bf16 v[144:159], v[248:251], v[252:255], v[144:159]
	s_waitcnt lgkmcnt(0)
	v_mfma_f32_32x32x16_bf16 v[160:175], v[202:205], v[244:247], v[160:175]
	ds_read_b64_tr_b16 v[202:203], v216 offset:40960
	ds_read_b64_tr_b16 v[204:205], v218 offset:40960
	ds_read_b64_tr_b16 v[244:245], v220 offset:40960
	ds_read_b64_tr_b16 v[246:247], v222 offset:40960
	ds_read_b64_tr_b16 v[248:249], v224 offset:40960
	ds_read_b64_tr_b16 v[250:251], v226 offset:40960
	ds_read_b64_tr_b16 v[252:253], v228 offset:40960
	ds_read_b64_tr_b16 v[254:255], v230 offset:40960
	s_cbranch_scc1 .Lat5_nomask
	s_nop 2
	v_cndmask_b32_e64 v180, v160, v242, s[2:3]
	v_cndmask_b32_e64 v198, v144, v242, s[2:3]
	v_cndmask_b32_e64 v161, v242, v161, s[4:5]
	v_cndmask_b32_e64 v160, v180, v160, s[4:5]
	v_cndmask_b32_e64 v145, v242, v145, s[4:5]
	v_cndmask_b32_e64 v144, v198, v144, s[4:5]
	v_cndmask_b32_e64 v162, v162, v242, s[6:7]
	v_cndmask_b32_e64 v146, v146, v242, s[6:7]
	v_cndmask_b32_e64 v163, v163, v242, s[8:9]
	v_cndmask_b32_e64 v147, v147, v242, s[8:9]
	v_cndmask_b32_e64 v164, v164, v242, s[10:11]
	v_cndmask_b32_e64 v148, v148, v242, s[10:11]
	v_cndmask_b32_e64 v165, v165, v242, s[12:13]
	v_cndmask_b32_e64 v149, v149, v242, s[12:13]
	v_cndmask_b32_e64 v166, v166, v242, s[14:15]
	v_cndmask_b32_e64 v150, v150, v242, s[14:15]
	v_cndmask_b32_e64 v167, v167, v242, s[16:17]
	v_cndmask_b32_e64 v151, v151, v242, s[16:17]
	v_cndmask_b32_e64 v168, v168, v242, s[18:19]
	v_cndmask_b32_e64 v152, v152, v242, s[18:19]
	v_cndmask_b32_e64 v169, v169, v242, s[20:21]
	v_cndmask_b32_e64 v153, v153, v242, s[20:21]
	v_cndmask_b32_e64 v170, v170, v242, s[22:23]
	v_cndmask_b32_e64 v154, v154, v242, s[22:23]
	v_cndmask_b32_e64 v171, v171, v242, s[24:25]
	v_cndmask_b32_e64 v155, v155, v242, s[24:25]
	v_cndmask_b32_e64 v172, v172, v242, s[26:27]
	v_cndmask_b32_e64 v156, v156, v242, s[26:27]
	v_cndmask_b32_e64 v173, v173, v242, s[28:29]
	v_cndmask_b32_e64 v157, v157, v242, s[28:29]
	v_cndmask_b32_e64 v174, v174, v242, s[30:31]
	v_cndmask_b32_e64 v158, v158, v242, s[30:31]
	v_cndmask_b32_e64 v175, v175, v242, s[34:35]
	v_cndmask_b32_e64 v159, v159, v242, s[34:35]
.Lat5_nomask:
	v_add_u32_e32 v215, s40, v185
	v_add_u32_e32 v215, 0x60, v215
	v_cvt_f32_i32_e32 v215, v215
	v_mul_f32_e32 v200, v184, v215
	v_max_f32_e32 v217, v144, v145
	v_max_f32_e32 v219, v160, v161
	v_max3_f32 v217, v217, v146, v147
	v_max3_f32 v219, v219, v162, v163
	v_max3_f32 v217, v217, v148, v149
	v_max3_f32 v219, v219, v164, v165
	v_max3_f32 v217, v217, v150, v151
	v_max3_f32 v219, v219, v166, v167
	v_max3_f32 v217, v217, v152, v153
	v_max3_f32 v219, v219, v168, v169
	v_max3_f32 v217, v217, v154, v155
	v_max3_f32 v219, v219, v170, v171
	v_max3_f32 v217, v217, v156, v157
	v_max3_f32 v219, v219, v172, v173
	v_max3_f32 v217, v217, v158, v159
	v_max3_f32 v219, v219, v174, v175
	v_mov_b32_e32 v221, v217
	v_mov_b32_e32 v223, v219
	v_add_f32_e32 v227, 0x41000000, v199
	v_add_f32_e32 v215, 0x41000000, v201
	v_permlane32_swap_b32_e32 v217, v221
	v_permlane32_swap_b32_e32 v219, v223
	v_max_f32_e32 v217, v217, v221
	v_max_f32_e32 v219, v219, v223
	v_add_f32_e32 v225, v200, v217
	v_add_f32_e32 v229, v200, v219
	v_cmp_gt_f32_e32 vcc, v225, v227
	v_cmp_gt_f32_e64 s[0:1], v229, v215
	s_or_b64 vcc, vcc, s[0:1]
	s_cbranch_vccz .Lat5_noresc
	v_max_f32_e32 v217, v199, v225
	v_max_f32_e32 v219, v201, v229
	v_sub_f32_e32 v221, v199, v217
	v_exp_f32_e32 v180, v221
	v_sub_f32_e32 v221, v201, v219
	v_exp_f32_e32 v198, v221
	v_mov_b32_e32 v201, v219
	v_mul_f32_e32 v197, v197, v180
	v_mul_f32_e32 v196, v196, v198
	v_pk_mul_f32 v[112:113], v[112:113], v[180:181] op_sel_hi:[1,0]
	v_pk_mul_f32 v[114:115], v[114:115], v[180:181] op_sel_hi:[1,0]
	v_pk_mul_f32 v[116:117], v[116:117], v[180:181] op_sel_hi:[1,0]
	v_pk_mul_f32 v[118:119], v[118:119], v[180:181] op_sel_hi:[1,0]
	v_pk_mul_f32 v[120:121], v[120:121], v[180:181] op_sel_hi:[1,0]
	v_pk_mul_f32 v[122:123], v[122:123], v[180:181] op_sel_hi:[1,0]
	v_pk_mul_f32 v[124:125], v[124:125], v[180:181] op_sel_hi:[1,0]
	v_pk_mul_f32 v[126:127], v[126:127], v[180:181] op_sel_hi:[1,0]
	v_pk_mul_f32 v[64:65], v[64:65], v[180:181] op_sel_hi:[1,0]
	v_pk_mul_f32 v[66:67], v[66:67], v[180:181] op_sel_hi:[1,0]
	v_pk_mul_f32 v[68:69], v[68:69], v[180:181] op_sel_hi:[1,0]
	v_pk_mul_f32 v[70:71], v[70:71], v[180:181] op_sel_hi:[1,0]
	v_pk_mul_f32 v[72:73], v[72:73], v[180:181] op_sel_hi:[1,0]
	v_pk_mul_f32 v[74:75], v[74:75], v[180:181] op_sel_hi:[1,0]
	v_pk_mul_f32 v[76:77], v[76:77], v[180:181] op_sel_hi:[1,0]
	v_pk_mul_f32 v[78:79], v[78:79], v[180:181] op_sel_hi:[1,0]
	v_pk_mul_f32 v[32:33], v[32:33], v[180:181] op_sel_hi:[1,0]
	v_pk_mul_f32 v[34:35], v[34:35], v[180:181] op_sel_hi:[1,0]
	v_pk_mul_f32 v[36:37], v[36:37], v[180:181] op_sel_hi:[1,0]
	v_pk_mul_f32 v[38:39], v[38:39], v[180:181] op_sel_hi:[1,0]
	v_pk_mul_f32 v[40:41], v[40:41], v[180:181] op_sel_hi:[1,0]
	v_pk_mul_f32 v[42:43], v[42:43], v[180:181] op_sel_hi:[1,0]
	v_pk_mul_f32 v[44:45], v[44:45], v[180:181] op_sel_hi:[1,0]
	v_pk_mul_f32 v[46:47], v[46:47], v[180:181] op_sel_hi:[1,0]
	v_pk_mul_f32 v[0:1], v[0:1], v[180:181] op_sel_hi:[1,0]
	v_pk_mul_f32 v[2:3], v[2:3], v[180:181] op_sel_hi:[1,0]
	v_pk_mul_f32 v[4:5], v[4:5], v[180:181] op_sel_hi:[1,0]
	v_pk_mul_f32 v[6:7], v[6:7], v[180:181] op_sel_hi:[1,0]
	v_pk_mul_f32 v[8:9], v[8:9], v[180:181] op_sel_hi:[1,0]
	v_pk_mul_f32 v[10:11], v[10:11], v[180:181] op_sel_hi:[1,0]
	v_pk_mul_f32 v[12:13], v[12:13], v[180:181] op_sel_hi:[1,0]
	v_pk_mul_f32 v[14:15], v[14:15], v[180:181] op_sel_hi:[1,0]
	v_pk_mul_f32 v[96:97], v[96:97], v[198:199] op_sel_hi:[1,0]
	v_pk_mul_f32 v[98:99], v[98:99], v[198:199] op_sel_hi:[1,0]
	v_pk_mul_f32 v[100:101], v[100:101], v[198:199] op_sel_hi:[1,0]
	v_pk_mul_f32 v[102:103], v[102:103], v[198:199] op_sel_hi:[1,0]
	v_pk_mul_f32 v[104:105], v[104:105], v[198:199] op_sel_hi:[1,0]
	v_pk_mul_f32 v[106:107], v[106:107], v[198:199] op_sel_hi:[1,0]
	v_pk_mul_f32 v[108:109], v[108:109], v[198:199] op_sel_hi:[1,0]
	v_pk_mul_f32 v[110:111], v[110:111], v[198:199] op_sel_hi:[1,0]
	v_pk_mul_f32 v[80:81], v[80:81], v[198:199] op_sel_hi:[1,0]
	v_pk_mul_f32 v[82:83], v[82:83], v[198:199] op_sel_hi:[1,0]
	v_pk_mul_f32 v[84:85], v[84:85], v[198:199] op_sel_hi:[1,0]
	v_pk_mul_f32 v[86:87], v[86:87], v[198:199] op_sel_hi:[1,0]
	v_pk_mul_f32 v[88:89], v[88:89], v[198:199] op_sel_hi:[1,0]
	v_pk_mul_f32 v[90:91], v[90:91], v[198:199] op_sel_hi:[1,0]
	v_pk_mul_f32 v[92:93], v[92:93], v[198:199] op_sel_hi:[1,0]
	v_pk_mul_f32 v[94:95], v[94:95], v[198:199] op_sel_hi:[1,0]
	v_pk_mul_f32 v[48:49], v[48:49], v[198:199] op_sel_hi:[1,0]
	v_pk_mul_f32 v[50:51], v[50:51], v[198:199] op_sel_hi:[1,0]
	v_pk_mul_f32 v[52:53], v[52:53], v[198:199] op_sel_hi:[1,0]
	v_pk_mul_f32 v[54:55], v[54:55], v[198:199] op_sel_hi:[1,0]
	v_pk_mul_f32 v[56:57], v[56:57], v[198:199] op_sel_hi:[1,0]
	v_pk_mul_f32 v[58:59], v[58:59], v[198:199] op_sel_hi:[1,0]
	v_pk_mul_f32 v[60:61], v[60:61], v[198:199] op_sel_hi:[1,0]
	v_pk_mul_f32 v[62:63], v[62:63], v[198:199] op_sel_hi:[1,0]
	v_pk_mul_f32 v[16:17], v[16:17], v[198:199] op_sel_hi:[1,0]
	v_pk_mul_f32 v[18:19], v[18:19], v[198:199] op_sel_hi:[1,0]
	v_pk_mul_f32 v[20:21], v[20:21], v[198:199] op_sel_hi:[1,0]
	v_pk_mul_f32 v[22:23], v[22:23], v[198:199] op_sel_hi:[1,0]
	v_pk_mul_f32 v[24:25], v[24:25], v[198:199] op_sel_hi:[1,0]
	v_pk_mul_f32 v[26:27], v[26:27], v[198:199] op_sel_hi:[1,0]
	v_pk_mul_f32 v[28:29], v[28:29], v[198:199] op_sel_hi:[1,0]
	v_pk_mul_f32 v[30:31], v[30:31], v[198:199] op_sel_hi:[1,0]
	v_mov_b32_e32 v199, v217
.Lat5_noresc:
	v_sub_f32_e32 v180, v200, v199
	v_sub_f32_e32 v198, v200, v201
	v_add_f32_e32 v144, v144, v180
	v_add_f32_e32 v160, v160, v198
	v_exp_f32_e32 v144, v144
	v_exp_f32_e32 v160, v160
	v_add_f32_e32 v145, v145, v180
	v_add_f32_e32 v161, v161, v198
	v_exp_f32_e32 v145, v145
	v_exp_f32_e32 v161, v161
	v_add_f32_e32 v146, v146, v180
	v_add_f32_e32 v162, v162, v198
	v_exp_f32_e32 v146, v146
	v_exp_f32_e32 v162, v162
	v_add_f32_e32 v147, v147, v180
	v_add_f32_e32 v163, v163, v198
	v_exp_f32_e32 v147, v147
	v_exp_f32_e32 v163, v163
	v_add_f32_e32 v148, v148, v180
	v_add_f32_e32 v164, v164, v198
	v_exp_f32_e32 v148, v148
	v_exp_f32_e32 v164, v164
	v_add_f32_e32 v149, v149, v180
	v_add_f32_e32 v165, v165, v198
	v_exp_f32_e32 v149, v149
	v_exp_f32_e32 v165, v165
	v_add_f32_e32 v150, v150, v180
	v_add_f32_e32 v166, v166, v198
	v_exp_f32_e32 v150, v150
	v_exp_f32_e32 v166, v166
	v_add_f32_e32 v151, v151, v180
	v_add_f32_e32 v167, v167, v198
	v_exp_f32_e32 v151, v151
	v_exp_f32_e32 v167, v167
	v_add_f32_e32 v215, v144, v145
	v_add_f32_e32 v217, v160, v161
	v_add_f32_e32 v215, v215, v146
	v_add_f32_e32 v217, v217, v162
	v_add_f32_e32 v215, v215, v147
	v_add_f32_e32 v217, v217, v163
	v_add_f32_e32 v215, v215, v148
	v_add_f32_e32 v217, v217, v164
	v_add_f32_e32 v215, v215, v149
	v_add_f32_e32 v217, v217, v165
	v_add_f32_e32 v215, v215, v150
	v_add_f32_e32 v217, v217, v166
	v_add_f32_e32 v215, v215, v151
	v_add_f32_e32 v217, v217, v167
	v_cvt_pk_bf16_f32 v144, v144, v145
	v_cvt_pk_bf16_f32 v160, v160, v161
	v_cvt_pk_bf16_f32 v145, v146, v147
	v_cvt_pk_bf16_f32 v161, v162, v163
	v_cvt_pk_bf16_f32 v146, v148, v149
	v_cvt_pk_bf16_f32 v162, v164, v165
	v_cvt_pk_bf16_f32 v147, v150, v151
	v_cvt_pk_bf16_f32 v163, v166, v167
	ds_read_b64_tr_b16 v[148:149], v216 offset:45056
	ds_read_b64_tr_b16 v[150:151], v218 offset:45056
	ds_read_b64_tr_b16 v[164:165], v220 offset:45056
	ds_read_b64_tr_b16 v[166:167], v222 offset:45056
	s_waitcnt lgkmcnt(4)
	v_mfma_f32_32x32x16_bf16 v[112:127], v[202:205], v[144:147], v[112:127]
	v_add_f32_e32 v152, v152, v180
	v_add_f32_e32 v168, v168, v198
	v_exp_f32_e32 v152, v152
	v_exp_f32_e32 v168, v168
	v_add_f32_e32 v153, v153, v180
	v_add_f32_e32 v169, v169, v198
	v_exp_f32_e32 v153, v153
	v_mfma_f32_32x32x16_bf16 v[96:111], v[202:205], v[160:163], v[96:111]
	v_exp_f32_e32 v169, v169
	v_add_f32_e32 v154, v154, v180
	v_add_f32_e32 v170, v170, v198
	v_exp_f32_e32 v154, v154
	v_exp_f32_e32 v170, v170
	v_add_f32_e32 v155, v155, v180
	v_add_f32_e32 v171, v171, v198
	ds_read_b64_tr_b16 v[202:203], v224 offset:45056
	ds_read_b64_tr_b16 v[204:205], v226 offset:45056
	v_mfma_f32_32x32x16_bf16 v[64:79], v[244:247], v[144:147], v[64:79]
	v_exp_f32_e32 v155, v155
	v_exp_f32_e32 v171, v171
	v_add_f32_e32 v156, v156, v180
	v_add_f32_e32 v172, v172, v198
	v_exp_f32_e32 v156, v156
	v_exp_f32_e32 v172, v172
	v_add_f32_e32 v157, v157, v180
	v_mfma_f32_32x32x16_bf16 v[80:95], v[244:247], v[160:163], v[80:95]
	v_add_f32_e32 v173, v173, v198
	v_exp_f32_e32 v157, v157
	v_exp_f32_e32 v173, v173
	v_add_f32_e32 v158, v158, v180
	v_add_f32_e32 v174, v174, v198
	v_exp_f32_e32 v158, v158
	v_exp_f32_e32 v174, v174
	ds_read_b64_tr_b16 v[244:245], v228 offset:45056
	ds_read_b64_tr_b16 v[246:247], v230 offset:45056
	v_mfma_f32_32x32x16_bf16 v[32:47], v[248:251], v[144:147], v[32:47]
	v_add_f32_e32 v159, v159, v180
	v_add_f32_e32 v175, v175, v198
	v_exp_f32_e32 v159, v159
	v_exp_f32_e32 v175, v175
	v_add_f32_e32 v215, v215, v152
	v_add_f32_e32 v217, v217, v168
	v_add_f32_e32 v215, v215, v153
	v_mfma_f32_32x32x16_bf16 v[48:63], v[248:251], v[160:163], v[48:63]
	v_add_f32_e32 v217, v217, v169
	v_add_f32_e32 v215, v215, v154
	v_add_f32_e32 v217, v217, v170
	v_add_f32_e32 v215, v215, v155
	v_add_f32_e32 v217, v217, v171
	v_add_f32_e32 v215, v215, v156
	v_add_f32_e32 v217, v217, v172
	v_mfma_f32_32x32x16_bf16 v[0:15], v[252:255], v[144:147], v[0:15]
	v_add_f32_e32 v215, v215, v157
	v_add_f32_e32 v217, v217, v173
	v_add_f32_e32 v215, v215, v158
	v_add_f32_e32 v217, v217, v174
	v_add_f32_e32 v215, v215, v159
	v_add_f32_e32 v217, v217, v175
	v_cvt_pk_bf16_f32 v152, v152, v153
	v_mfma_f32_32x32x16_bf16 v[16:31], v[252:255], v[160:163], v[16:31]
	v_cvt_pk_bf16_f32 v168, v168, v169
	v_cvt_pk_bf16_f32 v153, v154, v155
	v_cvt_pk_bf16_f32 v169, v170, v171
	v_cvt_pk_bf16_f32 v154, v156, v157
	v_cvt_pk_bf16_f32 v170, v172, v173
	v_cvt_pk_bf16_f32 v155, v158, v159
	v_cvt_pk_bf16_f32 v171, v174, v175
	v_add_f32_e32 v197, v197, v215
	v_add_f32_e32 v196, v196, v217
	s_waitcnt lgkmcnt(6)
	v_mfma_f32_32x32x16_bf16 v[112:127], v[148:151], v[152:155], v[112:127]
	v_mfma_f32_32x32x16_bf16 v[96:111], v[148:151], v[168:171], v[96:111]
	s_waitcnt lgkmcnt(4)
	v_mfma_f32_32x32x16_bf16 v[64:79], v[164:167], v[152:155], v[64:79]
	v_mfma_f32_32x32x16_bf16 v[80:95], v[164:167], v[168:171], v[80:95]
	s_waitcnt lgkmcnt(2)
	v_mfma_f32_32x32x16_bf16 v[32:47], v[202:205], v[152:155], v[32:47]
	v_mfma_f32_32x32x16_bf16 v[48:63], v[202:205], v[168:171], v[48:63]
	s_waitcnt lgkmcnt(0)
	v_mfma_f32_32x32x16_bf16 v[0:15], v[244:247], v[152:155], v[0:15]
	v_mfma_f32_32x32x16_bf16 v[16:31], v[244:247], v[168:171], v[16:31]
	s_cmp_gt_i32 s78, s84
	s_cbranch_scc1 .LBB0_753
.LBB0_805:
	ds_read_b128 v[160:163], v237 offset:32768
	ds_read_b128 v[164:167], v189
	ds_read_b128 v[202:205], v235 offset:32768
	ds_read_b128 v[244:247], v189 offset:4096
	ds_read_b128 v[248:251], v236 offset:32768
	ds_read_b128 v[252:255], v189 offset:1024
	s_cmp_lg_u32 s97, s40
	s_waitcnt lgkmcnt(4)
	v_mfma_f32_32x32x16_bf16 v[144:159], v[160:163], v[164:167], v[128:143]
	s_waitcnt lgkmcnt(2)
	v_mfma_f32_32x32x16_bf16 v[160:175], v[202:205], v[244:247], v[128:143]
	ds_read_b128 v[202:205], v234 offset:32768
	ds_read_b128 v[244:247], v189 offset:5120
	s_waitcnt lgkmcnt(2)
	v_mfma_f32_32x32x16_bf16 v[144:159], v[248:251], v[252:255], v[144:159]
	ds_read_b128 v[248:251], v241 offset:32768
	ds_read_b128 v[252:255], v189 offset:2048
	s_waitcnt lgkmcnt(2)
	v_mfma_f32_32x32x16_bf16 v[160:175], v[202:205], v[244:247], v[160:175]
	ds_read_b128 v[202:205], v239 offset:32768
	ds_read_b128 v[244:247], v189 offset:6144
	s_waitcnt lgkmcnt(2)
	v_mfma_f32_32x32x16_bf16 v[144:159], v[248:251], v[252:255], v[144:159]
	ds_read_b128 v[248:251], v240 offset:32768
	ds_read_b128 v[252:255], v189 offset:3072
	s_waitcnt lgkmcnt(2)
	v_mfma_f32_32x32x16_bf16 v[160:175], v[202:205], v[244:247], v[160:175]
	ds_read_b128 v[202:205], v238 offset:32768
	ds_read_b128 v[244:247], v189 offset:7168
	s_waitcnt lgkmcnt(2)
	v_mfma_f32_32x32x16_bf16 v[144:159], v[248:251], v[252:255], v[144:159]
	s_waitcnt lgkmcnt(0)
	v_mfma_f32_32x32x16_bf16 v[160:175], v[202:205], v[244:247], v[160:175]
	ds_read_b64_tr_b16 v[202:203], v216 offset:32768
	ds_read_b64_tr_b16 v[204:205], v218 offset:32768
	ds_read_b64_tr_b16 v[244:245], v220 offset:32768
	ds_read_b64_tr_b16 v[246:247], v222 offset:32768
	ds_read_b64_tr_b16 v[248:249], v224 offset:32768
	ds_read_b64_tr_b16 v[250:251], v226 offset:32768
	ds_read_b64_tr_b16 v[252:253], v228 offset:32768
	ds_read_b64_tr_b16 v[254:255], v230 offset:32768
	s_cbranch_scc1 .Lat6_nomask
	s_nop 2
	v_cndmask_b32_e64 v180, v160, v242, s[2:3]
	v_cndmask_b32_e64 v198, v144, v242, s[2:3]
	v_cndmask_b32_e64 v161, v242, v161, s[4:5]
	v_cndmask_b32_e64 v160, v180, v160, s[4:5]
	v_cndmask_b32_e64 v145, v242, v145, s[4:5]
	v_cndmask_b32_e64 v144, v198, v144, s[4:5]
	v_cndmask_b32_e64 v162, v162, v242, s[6:7]
	v_cndmask_b32_e64 v146, v146, v242, s[6:7]
	v_cndmask_b32_e64 v163, v163, v242, s[8:9]
	v_cndmask_b32_e64 v147, v147, v242, s[8:9]
	v_cndmask_b32_e64 v164, v164, v242, s[10:11]
	v_cndmask_b32_e64 v148, v148, v242, s[10:11]
	v_cndmask_b32_e64 v165, v165, v242, s[12:13]
	v_cndmask_b32_e64 v149, v149, v242, s[12:13]
	v_cndmask_b32_e64 v166, v166, v242, s[14:15]
	v_cndmask_b32_e64 v150, v150, v242, s[14:15]
	v_cndmask_b32_e64 v167, v167, v242, s[16:17]
	v_cndmask_b32_e64 v151, v151, v242, s[16:17]
	v_cndmask_b32_e64 v168, v168, v242, s[18:19]
	v_cndmask_b32_e64 v152, v152, v242, s[18:19]
	v_cndmask_b32_e64 v169, v169, v242, s[20:21]
	v_cndmask_b32_e64 v153, v153, v242, s[20:21]
	v_cndmask_b32_e64 v170, v170, v242, s[22:23]
	v_cndmask_b32_e64 v154, v154, v242, s[22:23]
	v_cndmask_b32_e64 v171, v171, v242, s[24:25]
	v_cndmask_b32_e64 v155, v155, v242, s[24:25]
	v_cndmask_b32_e64 v172, v172, v242, s[26:27]
	v_cndmask_b32_e64 v156, v156, v242, s[26:27]
	v_cndmask_b32_e64 v173, v173, v242, s[28:29]
	v_cndmask_b32_e64 v157, v157, v242, s[28:29]
	v_cndmask_b32_e64 v174, v174, v242, s[30:31]
	v_cndmask_b32_e64 v158, v158, v242, s[30:31]
	v_cndmask_b32_e64 v175, v175, v242, s[34:35]
	v_cndmask_b32_e64 v159, v159, v242, s[34:35]
.Lat6_nomask:
	v_add_u32_e32 v215, s40, v185
	v_add_u32_e32 v215, 0x40, v215
	v_cvt_f32_i32_e32 v215, v215
	v_mul_f32_e32 v200, v184, v215
	v_max_f32_e32 v217, v144, v145
	v_max_f32_e32 v219, v160, v161
	v_max3_f32 v217, v217, v146, v147
	v_max3_f32 v219, v219, v162, v163
	v_max3_f32 v217, v217, v148, v149
	v_max3_f32 v219, v219, v164, v165
	v_max3_f32 v217, v217, v150, v151
	v_max3_f32 v219, v219, v166, v167
	v_max3_f32 v217, v217, v152, v153
	v_max3_f32 v219, v219, v168, v169
	v_max3_f32 v217, v217, v154, v155
	v_max3_f32 v219, v219, v170, v171
	v_max3_f32 v217, v217, v156, v157
	v_max3_f32 v219, v219, v172, v173
	v_max3_f32 v217, v217, v158, v159
	v_max3_f32 v219, v219, v174, v175
	v_mov_b32_e32 v221, v217
	v_mov_b32_e32 v223, v219
	v_add_f32_e32 v227, 0x41000000, v199
	v_add_f32_e32 v215, 0x41000000, v201
	v_permlane32_swap_b32_e32 v217, v221
	v_permlane32_swap_b32_e32 v219, v223
	v_max_f32_e32 v217, v217, v221
	v_max_f32_e32 v219, v219, v223
	v_add_f32_e32 v225, v200, v217
	v_add_f32_e32 v229, v200, v219
	v_cmp_gt_f32_e32 vcc, v225, v227
	v_cmp_gt_f32_e64 s[0:1], v229, v215
	s_or_b64 vcc, vcc, s[0:1]
	s_cbranch_vccz .Lat6_noresc
	v_max_f32_e32 v217, v199, v225
	v_max_f32_e32 v219, v201, v229
	v_sub_f32_e32 v221, v199, v217
	v_exp_f32_e32 v180, v221
	v_sub_f32_e32 v221, v201, v219
	v_exp_f32_e32 v198, v221
	v_mov_b32_e32 v201, v219
	v_mul_f32_e32 v197, v197, v180
	v_mul_f32_e32 v196, v196, v198
	v_pk_mul_f32 v[112:113], v[112:113], v[180:181] op_sel_hi:[1,0]
	v_pk_mul_f32 v[114:115], v[114:115], v[180:181] op_sel_hi:[1,0]
	v_pk_mul_f32 v[116:117], v[116:117], v[180:181] op_sel_hi:[1,0]
	v_pk_mul_f32 v[118:119], v[118:119], v[180:181] op_sel_hi:[1,0]
	v_pk_mul_f32 v[120:121], v[120:121], v[180:181] op_sel_hi:[1,0]
	v_pk_mul_f32 v[122:123], v[122:123], v[180:181] op_sel_hi:[1,0]
	v_pk_mul_f32 v[124:125], v[124:125], v[180:181] op_sel_hi:[1,0]
	v_pk_mul_f32 v[126:127], v[126:127], v[180:181] op_sel_hi:[1,0]
	v_pk_mul_f32 v[64:65], v[64:65], v[180:181] op_sel_hi:[1,0]
	v_pk_mul_f32 v[66:67], v[66:67], v[180:181] op_sel_hi:[1,0]
	v_pk_mul_f32 v[68:69], v[68:69], v[180:181] op_sel_hi:[1,0]
	v_pk_mul_f32 v[70:71], v[70:71], v[180:181] op_sel_hi:[1,0]
	v_pk_mul_f32 v[72:73], v[72:73], v[180:181] op_sel_hi:[1,0]
	v_pk_mul_f32 v[74:75], v[74:75], v[180:181] op_sel_hi:[1,0]
	v_pk_mul_f32 v[76:77], v[76:77], v[180:181] op_sel_hi:[1,0]
	v_pk_mul_f32 v[78:79], v[78:79], v[180:181] op_sel_hi:[1,0]
	v_pk_mul_f32 v[32:33], v[32:33], v[180:181] op_sel_hi:[1,0]
	v_pk_mul_f32 v[34:35], v[34:35], v[180:181] op_sel_hi:[1,0]
	v_pk_mul_f32 v[36:37], v[36:37], v[180:181] op_sel_hi:[1,0]
	v_pk_mul_f32 v[38:39], v[38:39], v[180:181] op_sel_hi:[1,0]
	v_pk_mul_f32 v[40:41], v[40:41], v[180:181] op_sel_hi:[1,0]
	v_pk_mul_f32 v[42:43], v[42:43], v[180:181] op_sel_hi:[1,0]
	v_pk_mul_f32 v[44:45], v[44:45], v[180:181] op_sel_hi:[1,0]
	v_pk_mul_f32 v[46:47], v[46:47], v[180:181] op_sel_hi:[1,0]
	v_pk_mul_f32 v[0:1], v[0:1], v[180:181] op_sel_hi:[1,0]
	v_pk_mul_f32 v[2:3], v[2:3], v[180:181] op_sel_hi:[1,0]
	v_pk_mul_f32 v[4:5], v[4:5], v[180:181] op_sel_hi:[1,0]
	v_pk_mul_f32 v[6:7], v[6:7], v[180:181] op_sel_hi:[1,0]
	v_pk_mul_f32 v[8:9], v[8:9], v[180:181] op_sel_hi:[1,0]
	v_pk_mul_f32 v[10:11], v[10:11], v[180:181] op_sel_hi:[1,0]
	v_pk_mul_f32 v[12:13], v[12:13], v[180:181] op_sel_hi:[1,0]
	v_pk_mul_f32 v[14:15], v[14:15], v[180:181] op_sel_hi:[1,0]
	v_pk_mul_f32 v[96:97], v[96:97], v[198:199] op_sel_hi:[1,0]
	v_pk_mul_f32 v[98:99], v[98:99], v[198:199] op_sel_hi:[1,0]
	v_pk_mul_f32 v[100:101], v[100:101], v[198:199] op_sel_hi:[1,0]
	v_pk_mul_f32 v[102:103], v[102:103], v[198:199] op_sel_hi:[1,0]
	v_pk_mul_f32 v[104:105], v[104:105], v[198:199] op_sel_hi:[1,0]
	v_pk_mul_f32 v[106:107], v[106:107], v[198:199] op_sel_hi:[1,0]
	v_pk_mul_f32 v[108:109], v[108:109], v[198:199] op_sel_hi:[1,0]
	v_pk_mul_f32 v[110:111], v[110:111], v[198:199] op_sel_hi:[1,0]
	v_pk_mul_f32 v[80:81], v[80:81], v[198:199] op_sel_hi:[1,0]
	v_pk_mul_f32 v[82:83], v[82:83], v[198:199] op_sel_hi:[1,0]
	v_pk_mul_f32 v[84:85], v[84:85], v[198:199] op_sel_hi:[1,0]
	v_pk_mul_f32 v[86:87], v[86:87], v[198:199] op_sel_hi:[1,0]
	v_pk_mul_f32 v[88:89], v[88:89], v[198:199] op_sel_hi:[1,0]
	v_pk_mul_f32 v[90:91], v[90:91], v[198:199] op_sel_hi:[1,0]
	v_pk_mul_f32 v[92:93], v[92:93], v[198:199] op_sel_hi:[1,0]
	v_pk_mul_f32 v[94:95], v[94:95], v[198:199] op_sel_hi:[1,0]
	v_pk_mul_f32 v[48:49], v[48:49], v[198:199] op_sel_hi:[1,0]
	v_pk_mul_f32 v[50:51], v[50:51], v[198:199] op_sel_hi:[1,0]
	v_pk_mul_f32 v[52:53], v[52:53], v[198:199] op_sel_hi:[1,0]
	v_pk_mul_f32 v[54:55], v[54:55], v[198:199] op_sel_hi:[1,0]
	v_pk_mul_f32 v[56:57], v[56:57], v[198:199] op_sel_hi:[1,0]
	v_pk_mul_f32 v[58:59], v[58:59], v[198:199] op_sel_hi:[1,0]
	v_pk_mul_f32 v[60:61], v[60:61], v[198:199] op_sel_hi:[1,0]
	v_pk_mul_f32 v[62:63], v[62:63], v[198:199] op_sel_hi:[1,0]
	v_pk_mul_f32 v[16:17], v[16:17], v[198:199] op_sel_hi:[1,0]
	v_pk_mul_f32 v[18:19], v[18:19], v[198:199] op_sel_hi:[1,0]
	v_pk_mul_f32 v[20:21], v[20:21], v[198:199] op_sel_hi:[1,0]
	v_pk_mul_f32 v[22:23], v[22:23], v[198:199] op_sel_hi:[1,0]
	v_pk_mul_f32 v[24:25], v[24:25], v[198:199] op_sel_hi:[1,0]
	v_pk_mul_f32 v[26:27], v[26:27], v[198:199] op_sel_hi:[1,0]
	v_pk_mul_f32 v[28:29], v[28:29], v[198:199] op_sel_hi:[1,0]
	v_pk_mul_f32 v[30:31], v[30:31], v[198:199] op_sel_hi:[1,0]
	v_mov_b32_e32 v199, v217
.Lat6_noresc:
	v_sub_f32_e32 v180, v200, v199
	v_sub_f32_e32 v198, v200, v201
	v_add_f32_e32 v144, v144, v180
	v_add_f32_e32 v160, v160, v198
	v_exp_f32_e32 v144, v144
	v_exp_f32_e32 v160, v160
	v_add_f32_e32 v145, v145, v180
	v_add_f32_e32 v161, v161, v198
	v_exp_f32_e32 v145, v145
	v_exp_f32_e32 v161, v161
	v_add_f32_e32 v146, v146, v180
	v_add_f32_e32 v162, v162, v198
	v_exp_f32_e32 v146, v146
	v_exp_f32_e32 v162, v162
	v_add_f32_e32 v147, v147, v180
	v_add_f32_e32 v163, v163, v198
	v_exp_f32_e32 v147, v147
	v_exp_f32_e32 v163, v163
	v_add_f32_e32 v148, v148, v180
	v_add_f32_e32 v164, v164, v198
	v_exp_f32_e32 v148, v148
	v_exp_f32_e32 v164, v164
	v_add_f32_e32 v149, v149, v180
	v_add_f32_e32 v165, v165, v198
	v_exp_f32_e32 v149, v149
	v_exp_f32_e32 v165, v165
	v_add_f32_e32 v150, v150, v180
	v_add_f32_e32 v166, v166, v198
	v_exp_f32_e32 v150, v150
	v_exp_f32_e32 v166, v166
	v_add_f32_e32 v151, v151, v180
	v_add_f32_e32 v167, v167, v198
	v_exp_f32_e32 v151, v151
	v_exp_f32_e32 v167, v167
	v_add_f32_e32 v215, v144, v145
	v_add_f32_e32 v217, v160, v161
	v_add_f32_e32 v215, v215, v146
	v_add_f32_e32 v217, v217, v162
	v_add_f32_e32 v215, v215, v147
	v_add_f32_e32 v217, v217, v163
	v_add_f32_e32 v215, v215, v148
	v_add_f32_e32 v217, v217, v164
	v_add_f32_e32 v215, v215, v149
	v_add_f32_e32 v217, v217, v165
	v_add_f32_e32 v215, v215, v150
	v_add_f32_e32 v217, v217, v166
	v_add_f32_e32 v215, v215, v151
	v_add_f32_e32 v217, v217, v167
	v_cvt_pk_bf16_f32 v144, v144, v145
	v_cvt_pk_bf16_f32 v160, v160, v161
	v_cvt_pk_bf16_f32 v145, v146, v147
	v_cvt_pk_bf16_f32 v161, v162, v163
	v_cvt_pk_bf16_f32 v146, v148, v149
	v_cvt_pk_bf16_f32 v162, v164, v165
	v_cvt_pk_bf16_f32 v147, v150, v151
	v_cvt_pk_bf16_f32 v163, v166, v167
	ds_read_b64_tr_b16 v[148:149], v216 offset:36864
	ds_read_b64_tr_b16 v[150:151], v218 offset:36864
	ds_read_b64_tr_b16 v[164:165], v220 offset:36864
	ds_read_b64_tr_b16 v[166:167], v222 offset:36864
	s_waitcnt lgkmcnt(4)
	v_mfma_f32_32x32x16_bf16 v[112:127], v[202:205], v[144:147], v[112:127]
	v_add_f32_e32 v152, v152, v180
	v_add_f32_e32 v168, v168, v198
	v_exp_f32_e32 v152, v152
	v_exp_f32_e32 v168, v168
	v_add_f32_e32 v153, v153, v180
	v_add_f32_e32 v169, v169, v198
	v_exp_f32_e32 v153, v153
	v_mfma_f32_32x32x16_bf16 v[96:111], v[202:205], v[160:163], v[96:111]
	v_exp_f32_e32 v169, v169
	v_add_f32_e32 v154, v154, v180
	v_add_f32_e32 v170, v170, v198
	v_exp_f32_e32 v154, v154
	v_exp_f32_e32 v170, v170
	v_add_f32_e32 v155, v155, v180
	v_add_f32_e32 v171, v171, v198
	ds_read_b64_tr_b16 v[202:203], v224 offset:36864
	ds_read_b64_tr_b16 v[204:205], v226 offset:36864
	v_mfma_f32_32x32x16_bf16 v[64:79], v[244:247], v[144:147], v[64:79]
	v_exp_f32_e32 v155, v155
	v_exp_f32_e32 v171, v171
	v_add_f32_e32 v156, v156, v180
	v_add_f32_e32 v172, v172, v198
	v_exp_f32_e32 v156, v156
	v_exp_f32_e32 v172, v172
	v_add_f32_e32 v157, v157, v180
	v_mfma_f32_32x32x16_bf16 v[80:95], v[244:247], v[160:163], v[80:95]
	v_add_f32_e32 v173, v173, v198
	v_exp_f32_e32 v157, v157
	v_exp_f32_e32 v173, v173
	v_add_f32_e32 v158, v158, v180
	v_add_f32_e32 v174, v174, v198
	v_exp_f32_e32 v158, v158
	v_exp_f32_e32 v174, v174
	ds_read_b64_tr_b16 v[244:245], v228 offset:36864
	ds_read_b64_tr_b16 v[246:247], v230 offset:36864
	v_mfma_f32_32x32x16_bf16 v[32:47], v[248:251], v[144:147], v[32:47]
	v_add_f32_e32 v159, v159, v180
	v_add_f32_e32 v175, v175, v198
	v_exp_f32_e32 v159, v159
	v_exp_f32_e32 v175, v175
	v_add_f32_e32 v215, v215, v152
	v_add_f32_e32 v217, v217, v168
	v_add_f32_e32 v215, v215, v153
	v_mfma_f32_32x32x16_bf16 v[48:63], v[248:251], v[160:163], v[48:63]
	v_add_f32_e32 v217, v217, v169
	v_add_f32_e32 v215, v215, v154
	v_add_f32_e32 v217, v217, v170
	v_add_f32_e32 v215, v215, v155
	v_add_f32_e32 v217, v217, v171
	v_add_f32_e32 v215, v215, v156
	v_add_f32_e32 v217, v217, v172
	v_mfma_f32_32x32x16_bf16 v[0:15], v[252:255], v[144:147], v[0:15]
	v_add_f32_e32 v215, v215, v157
	v_add_f32_e32 v217, v217, v173
	v_add_f32_e32 v215, v215, v158
	v_add_f32_e32 v217, v217, v174
	v_add_f32_e32 v215, v215, v159
	v_add_f32_e32 v217, v217, v175
	v_cvt_pk_bf16_f32 v152, v152, v153
	v_mfma_f32_32x32x16_bf16 v[16:31], v[252:255], v[160:163], v[16:31]
	v_cvt_pk_bf16_f32 v168, v168, v169
	v_cvt_pk_bf16_f32 v153, v154, v155
	v_cvt_pk_bf16_f32 v169, v170, v171
	v_cvt_pk_bf16_f32 v154, v156, v157
	v_cvt_pk_bf16_f32 v170, v172, v173
	v_cvt_pk_bf16_f32 v155, v158, v159
	v_cvt_pk_bf16_f32 v171, v174, v175
	v_add_f32_e32 v197, v197, v215
	v_add_f32_e32 v196, v196, v217
	s_waitcnt lgkmcnt(6)
	v_mfma_f32_32x32x16_bf16 v[112:127], v[148:151], v[152:155], v[112:127]
	v_mfma_f32_32x32x16_bf16 v[96:111], v[148:151], v[168:171], v[96:111]
	s_waitcnt lgkmcnt(4)
	v_mfma_f32_32x32x16_bf16 v[64:79], v[164:167], v[152:155], v[64:79]
	v_mfma_f32_32x32x16_bf16 v[80:95], v[164:167], v[168:171], v[80:95]
	s_waitcnt lgkmcnt(2)
	v_mfma_f32_32x32x16_bf16 v[32:47], v[202:205], v[152:155], v[32:47]
	v_mfma_f32_32x32x16_bf16 v[48:63], v[202:205], v[168:171], v[48:63]
	s_waitcnt lgkmcnt(0)
	v_mfma_f32_32x32x16_bf16 v[0:15], v[244:247], v[152:155], v[0:15]
	v_mfma_f32_32x32x16_bf16 v[16:31], v[244:247], v[168:171], v[16:31]
	s_branch .LBB0_753

	.amdhsa_kernel _Z8yoco_fwd4Args
		.amdhsa_group_segment_fixed_size 0
		.amdhsa_private_segment_fixed_size 0
		.amdhsa_kernarg_size 416
		.amdhsa_user_sgpr_count 2
		.amdhsa_user_sgpr_dispatch_ptr 0
		.amdhsa_user_sgpr_queue_ptr 0
		.amdhsa_user_sgpr_kernarg_segment_ptr 1
		.amdhsa_user_sgpr_dispatch_id 0
		.amdhsa_user_sgpr_kernarg_preload_length 0
		.amdhsa_user_sgpr_kernarg_preload_offset 0
		.amdhsa_user_sgpr_private_segment_size 0
		.amdhsa_uses_dynamic_stack 0
		.amdhsa_enable_private_segment 0
		.amdhsa_system_sgpr_workgroup_id_x 1
		.amdhsa_system_sgpr_workgroup_id_y 0
		.amdhsa_system_sgpr_workgroup_id_z 0
		.amdhsa_system_sgpr_workgroup_info 0
		.amdhsa_system_vgpr_workitem_id 2
		.amdhsa_next_free_vgpr 256
		.amdhsa_next_free_sgpr 98
		.amdhsa_accum_offset 256
		.amdhsa_reserve_vcc 1
		.amdhsa_float_round_mode_32 0
		.amdhsa_float_round_mode_16_64 0
		.amdhsa_float_denorm_mode_32 3
		.amdhsa_float_denorm_mode_16_64 3
		.amdhsa_dx10_clamp 1
		.amdhsa_ieee_mode 1
		.amdhsa_fp16_overflow 0
		.amdhsa_tg_split 0
		.amdhsa_exception_fp_ieee_invalid_op 0
		.amdhsa_exception_fp_denorm_src 0
		.amdhsa_exception_fp_ieee_div_zero 0
		.amdhsa_exception_fp_ieee_overflow 0
		.amdhsa_exception_fp_ieee_underflow 0
		.amdhsa_exception_fp_ieee_inexact 0
		.amdhsa_exception_int_div_zero 0
	.end_amdhsa_kernel

amdhsa.kernels:
  - .agpr_count:     0
    .args:
      - .offset:         0
        .size:           160
        .value_kind:     by_value
      - .offset:         160
        .size:           4
        .value_kind:     hidden_block_count_x
      - .offset:         164
        .size:           4
        .value_kind:     hidden_block_count_y
      - .offset:         168
        .size:           4
        .value_kind:     hidden_block_count_z
      - .offset:         172
        .size:           2
        .value_kind:     hidden_group_size_x
      - .offset:         174
        .size:           2
        .value_kind:     hidden_group_size_y
      - .offset:         176
        .size:           2
        .value_kind:     hidden_group_size_z
      - .offset:         178
        .size:           2
        .value_kind:     hidden_remainder_x
      - .offset:         180
        .size:           2
        .value_kind:     hidden_remainder_y
      - .offset:         182
        .size:           2
        .value_kind:     hidden_remainder_z
      - .offset:         200
        .size:           8
        .value_kind:     hidden_global_offset_x
      - .offset:         208
        .size:           8
        .value_kind:     hidden_global_offset_y
      - .offset:         216
        .size:           8
        .value_kind:     hidden_global_offset_z
      - .offset:         224
        .size:           2
        .value_kind:     hidden_grid_dims
      - .offset:         248
        .size:           8
        .value_kind:     hidden_multigrid_sync_arg
      - .offset:         280
        .size:           4
        .value_kind:     hidden_dynamic_lds_size
    .group_segment_fixed_size: 0
    .kernarg_segment_align: 8
    .kernarg_segment_size: 416
    .language:       OpenCL C
    .language_version:
      - 2
      - 0
    .max_flat_workgroup_size: 512
    .name:           _Z8yoco_fwd4Args
    .private_segment_fixed_size: 0
    .sgpr_count:     104
    .sgpr_spill_count: 9
    .symbol:         _Z8yoco_fwd4Args.kd
    .uniform_work_group_size: 1
    .uses_dynamic_stack: false
    .vgpr_count:     256
    .vgpr_spill_count: 0
    .wavefront_size: 64
